# GQA main loop: LDS-DMA issue spread over 4 program points by wave group (SIMD partners in different groups)
# baseline (speedup 1.0000x reference)
;     const int tid = opaque_tid(), lane = tid & 63, r32 = lane & 31, hi = lane >> 5; const int wid = __builtin_amdgcn_readfirstlane(tid >> 6);
;     const bf16_t* Qw = Q + (long)(wid * QBLK) * PITCH;
;     const unsigned lds0 = (unsigned)(uintptr_t)shm;
;     float* wsf = (float*)(shm + LDS_WS) + wid * 64;
;     const unsigned kvo = (unsigned)((lane * PITCH + wid * 8) * 2);
;     const unsigned vvo = (unsigned)(((16 * (wid & 3) + (lane >> 2)) * PITCH + (wid >> 2) * 32 + (lane & 3) * 8) * 2);
;     const unsigned kdst = lds0 + LDS_K + wid * 1024, vdst = lds0 + LDS_V + wid * 1024;
;     ...
;     const char* Kbase = shm + LDS_K; bf16x8 kf[8];
;     const lds_cptr shm3 = (lds_cptr)shm; const lds_cptr kp0 = shm3 + LDS_K + hi * 1024 + r32 * 16; const lds_cptr vp0 = shm3 + LDS_V + ((lane >> 4) & 1) * 32 + (lane & 3) * 8 + (4 * hi + ((lane & 15) >> 2)) * 64;
;     DMA_K(0, 0); DMA_V(0, 0); DMA_K(1, SLOTB);
;     bf16x8 qr[4];
; #pragma unroll
;     for (int d0 = 0; d0 < 4; ++d0) qr[d0] = *reinterpret_cast<const bf16x8*>(&Qw[(long)r32 * PITCH + d0 * 16 + hi * 8]);
;     float mhat = (MODE == 0) ? bref : 0.f, l_reg = 0.f; f32x16 o[2]; o[0] = f32x16{}; o[1] = f32x16{}; f32x16 negm = f32x16{};
;     if (MODE == 0) { _Pragma("unroll") for (int r = 0; r < 16; ++r) negm[r] = -bref; }
;     if (MODE != 1) asm volatile("" : "+v"(negm));
;     int na_gr = 0, na_rs = 0, na_qc = 0, na_cs = 0;
;     if (MODE == 1) { na_gr = r0 + (wid >> 1); na_rs = min(max(na_gr - 4, 0), 120); na_qc = 32 * (wid & 1) + r32; na_cs = min(max(na_qc - 8, 0), 48); }
;     ...
;     bool resc = false;
;     ...
;     f32x16 pA0, pA1, pB0, pB1;
;     int sl_prev = 0, sl_cur = 0, sl_next = SLOTB;
;     ...
;     DMA_K(2, 2 * SLOTB);
;     WAIT_BAR(3);
;     qkt(pA0, pA1, Kbase, qr, negm, r32, hi); asm volatile("s_nop 15\n\ts_nop 7" : "+v"(pA0), "+v"(pA1));
;     START(pA0, pA1);
; __global__ void __launch_bounds__(NTHREADS, 2) mega_fwd(Params P) {
;     ...
;                     const int qb = idx / 12, r12 = idx % 12, b = r12 / 6, h = r12 % 6; const size_t rb = (size_t)b * RPB;
;                     ap::unit<8, 0>(qkv + (rb + 256 * qb) * DIN + C_QC + 64 * h, qkv + rb * DIN + C_KC + 64 * (h / 3), qkv + rb * DIN + C_VC + 64 * (h / 3),
;                                    omix + (rb + 256 * qb) * DM + 640 + 64 * h, ssb + (rb + 256 * qb) * 4 + 2, 132, (char*)lds, 0, 0, tcos[4096 + l]);
.LBB0_874:
	s_andn2_b64 vcc, exec, s[0:1]
	s_cbranch_vccnz .LBB0_439
	s_mul_hi_i32 s0, s48, 0x2aaaaaab
	s_lshr_b32 s1, s0, 31
	s_ashr_i32 s3, s0, 1
	s_add_i32 s3, s3, s1
	s_mul_i32 s0, s3, 12
	s_sub_i32 s0, s48, s0
	s_mul_i32 s1, s0, 43
	s_bfe_u32 s2, s1, 0x1000f
	s_bfe_u32 s1, s1, 0x80008
	s_add_i32 s1, s1, s2
	s_sext_i32_i8 s18, s1
	s_mul_i32 s1, s1, 6
	s_mul_i32 s9, s18, 0x2100
	s_lshl_b32 s4, s3, 8
	s_sub_i32 s8, s0, s1
	s_ashr_i32 s5, s9, 31
	s_ashr_i32 s6, s4, 31
	s_add_u32 s4, s9, s4
	s_addc_u32 s5, s5, s6
	s_mul_i32 s6, s5, 0x1200
	s_mul_hi_u32 s7, s4, 0x1200
	s_mov_b64 s[0:1], s[76:77]
	s_add_i32 s7, s7, s6
	s_mul_i32 s6, s4, 0x1200
	s_sext_i32_i8 s2, s8
	s_add_u32 s10, s0, s6
	s_addc_u32 s11, s1, s7
	s_lshl_b32 s0, s2, 6
	s_ashr_i32 s1, s0, 31
	s_lshl_b64 s[6:7], s[0:1], 1
	s_add_u32 s26, s10, s6
	s_addc_u32 s27, s11, s7
	s_mov_b64 s[0:1], s[76:77]
	s_mul_i32 s10, s18, 0x2520000
	s_mul_hi_i32 s9, s9, 0x1200
	s_add_u32 s2, s0, s10
	s_addc_u32 s22, s1, s9
	s_bfe_i32 s0, s8, 0x80000
	s_mulk_i32 s0, 0x56
	s_bfe_u32 s1, s0, 0x1000f
	s_bfe_u32 s0, s0, 0x80008
	s_add_i32 s0, s0, s1
	s_sext_i32_i8 s0, s0
	s_lshl_b32 s0, s0, 6
	s_ashr_i32 s1, s0, 31
	s_lshl_b64 s[16:17], s[0:1], 1
	s_add_u32 s30, s2, s16
	s_addc_u32 s34, s22, s17
	s_add_u32 s14, s30, 0xe400300
	s_addc_u32 s15, s34, 0
	s_mov_b64 s[0:1], s[76:77]
	s_add_u32 s23, s0, s10
	s_addc_u32 s24, s1, s9
	s_add_u32 s35, s23, s16
	s_addc_u32 s36, s24, s17
	v_readlane_b32 s20, v252, 9
	s_add_u32 s12, s35, 0xe401100
	s_mov_b64 s[10:11], s[76:77]
	s_mov_b64 s[8:9], s[76:77]
	s_mov_b64 s[0:1], s[76:77]
	v_readlane_b32 s21, v252, 10
	s_addc_u32 s13, s36, 0
	s_lshl_b64 s[20:21], s[20:21], 2
	s_add_u32 s0, s0, s20
	s_addc_u32 s1, s1, s21
	v_mov_b32_e32 v0, s0
	s_mov_b32 s0, 0x184000
	v_mov_b32_e32 v3, s1
	v_add_co_u32_e32 v2, vcc, s0, v0
	v_mov_b32_e32 v194, 0
	s_nop 0
	v_addc_co_u32_e32 v3, vcc, 0, v3, vcc
	flat_load_dword v6, v[2:3]
	v_mov_b32 v14, v214
	s_waitcnt vmcnt(0) lgkmcnt(0)
	v_xor_b32_e32 v50, 0x80000000, v6
	v_readfirstlane_b32 s25, v14
	s_ashr_i32 s19, s25, 6
	s_lshr_b32 s40, s19, 2
	s_add_i32 s40, s40, s19
	s_and_b32 s40, s40, 3
	s_lshl_b32 s0, s19, 5
	s_ashr_i32 s1, s0, 31
	s_mul_i32 s20, s19, 0x24000
	s_mul_hi_i32 s21, s0, 0x1200
	s_add_u32 s28, s26, s20
	s_addc_u32 s29, s27, s21
	s_lshl_b32 s20, s19, 4
	v_and_b32_e32 v15, 63, v14
	v_mov_b32_e32 v0, s20
	v_mad_u32_u24 v193, v15, s80, v0
	v_bfe_u32 v0, v14, 2, 4
	v_and_or_b32 v0, s20, 48, v0
	s_ashr_i32 s20, s25, 3
	s_and_b32 s20, s20, 0x7fffffe0
	v_mov_b32_e32 v2, s20
	v_mad_u32_u24 v0, v0, s81, v2
	v_lshlrev_b32_e32 v2, 3, v14
	v_and_b32_e32 v187, 24, v2
	v_and_b32_e32 v17, 31, v14
	v_or_b32_e32 v0, v0, v187
	s_lshl_b32 s21, s19, 10
	v_lshlrev_b32_e32 v192, 1, v0
	s_cmp_lg_u32 0, -1
	v_mul_u32_u24_e32 v0, 0x900, v17
	v_bfe_u32 v186, v14, 5, 1
	s_cselect_b32 s20, 0, 0
	v_lshlrev_b32_e32 v0, 1, v0
	s_add_i32 s26, s21, s20
	v_lshl_or_b32 v0, v186, 4, v0
	s_add_i32 s20, s26, 0x6000
	s_mov_b32 s27, m0
	s_mov_b32 m0, s26
	s_nop 0
	global_load_lds_dwordx4 v193, s[14:15]
	s_mov_b32 m0, s27
	v_lshl_add_u64 v[2:3], s[28:29], 0, v[0:1]
	s_mov_b32 s27, m0
	s_mov_b32 m0, s20
	s_nop 0
	global_load_lds_dwordx4 v192, s[12:13]
	s_mov_b32 m0, s27
	s_add_u32 s38, s30, 0xe448300
	v_add_co_u32_e32 v4, vcc, s82, v2
	s_addc_u32 s39, s34, 0
	s_add_i32 s27, s26, 0x2000
	s_mov_b32 s31, m0
	s_mov_b32 m0, s27
	s_nop 0
	global_load_lds_dwordx4 v193, s[38:39]
	s_mov_b32 m0, s31
	v_addc_co_u32_e32 v5, vcc, 0, v3, vcc
	flat_load_dwordx4 v[162:165], v[4:5]
	s_mov_b64 s[28:29], 0xe400000
	v_lshl_add_u64 v[2:3], v[2:3], 0, s[28:29]
	flat_load_dwordx4 v[158:161], v[2:3] offset:32
	flat_load_dwordx4 v[154:157], v[2:3] offset:64
	flat_load_dwordx4 v[150:153], v[2:3] offset:96
	v_mov_b32_e32 v51, v50
	v_mov_b32_e32 v52, v50
	v_mov_b32_e32 v53, v50
	v_mov_b32_e32 v54, v50
	v_mov_b32_e32 v55, v50
	v_mov_b32_e32 v56, v50
	v_mov_b32_e32 v57, v50
	v_mov_b32_e32 v58, v50
	v_mov_b32_e32 v59, v50
	v_mov_b32_e32 v60, v50
	v_mov_b32_e32 v61, v50
	v_mov_b32_e32 v62, v50
	v_mov_b32_e32 v63, v50
	v_mov_b32_e32 v64, v50
	v_mov_b32_e32 v65, v50
	s_add_u32 s28, s30, 0xe490300
	v_lshlrev_b32_e32 v0, 10, v186
	v_lshlrev_b32_e32 v4, 4, v17
	s_addc_u32 s29, s34, 0
	s_add_i32 s27, s26, 0x4000
	s_mov_b32 s31, m0
	s_mov_b32 m0, s27
	s_nop 0
	global_load_lds_dwordx4 v193, s[28:29]
	s_mov_b32 m0, s31
	v_add3_u32 v191, 0, v0, v4
	s_waitcnt vmcnt(3) lgkmcnt(0)
	s_barrier
	ds_read_b128 v[2:5], v191
	ds_read_b128 v[6:9], v191 offset:512
	s_waitcnt vmcnt(0) lgkmcnt(0)
	v_mfma_f32_32x32x16_bf16 v[34:49], v[2:5], v[162:165], v[50:65]
	s_add_u32 s38, s30, 0xe4d8300
	s_addc_u32 s39, s34, 0
	s_add_u32 s34, s35, 0xe449100
	s_addc_u32 s35, s36, 0
	v_lshlrev_b32_e32 v0, 1, v14
	v_and_b32_e32 v188, 32, v0
	v_lshlrev_b32_e32 v0, 8, v186
	v_mfma_f32_32x32x16_bf16 v[18:33], v[6:9], v[162:165], v[50:65]
	ds_read_b128 v[2:5], v191 offset:2048
	ds_read_b128 v[6:9], v191 offset:2560
	s_mov_b32 s31, 0
	s_mov_b32 s27, -1
	s_movk_i32 s29, 0x2000
	s_movk_i32 s28, 0x4000
	s_waitcnt lgkmcnt(1)
	v_mfma_f32_32x32x16_bf16 v[34:49], v[2:5], v[158:161], v[34:49]
	s_waitcnt lgkmcnt(0)
	v_mfma_f32_32x32x16_bf16 v[18:33], v[6:9], v[158:161], v[18:33]
	ds_read_b128 v[2:5], v191 offset:4096
	ds_read_b128 v[6:9], v191 offset:4608
	s_waitcnt lgkmcnt(1)
	v_mfma_f32_32x32x16_bf16 v[34:49], v[2:5], v[154:157], v[34:49]
	s_waitcnt lgkmcnt(0)
	v_mfma_f32_32x32x16_bf16 v[18:33], v[6:9], v[154:157], v[18:33]
	ds_read_b128 v[2:5], v191 offset:6144
	ds_read_b128 v[6:9], v191 offset:6656
	s_waitcnt lgkmcnt(1)
	v_mfma_f32_32x32x16_bf16 v[34:49], v[2:5], v[150:153], v[34:49]
	v_lshlrev_b32_e32 v3, 4, v14
	v_add_u32_e32 v2, 0, v188
	v_and_or_b32 v189, v3, s83, v0
	v_add3_u32 v190, v2, v187, v189
	s_waitcnt lgkmcnt(0)
	v_mfma_f32_32x32x16_bf16 v[18:33], v[6:9], v[150:153], v[18:33]
	s_nop 15
	s_nop 7
	s_waitcnt vmcnt(0) lgkmcnt(0)
	s_barrier
; #define WAIT_BAR(N) asm volatile("s_waitcnt vmcnt(" #N ") lgkmcnt(0)\n\ts_barrier" ::: "memory")
; #define DMA_K(t, slot) glds16s(kvo, Kh + (long)TROW(t) * PITCH, (unsigned)__builtin_amdgcn_readfirstlane(kdst + (slot)))
; #define DMA_V(t, slot) glds16s(vvo, Vh + (long)TROW(t) * PITCH, (unsigned)__builtin_amdgcn_readfirstlane(vdst + (slot)))
; #define ROT() do { sl_prev = sl_cur; sl_cur = sl_next; sl_next = (sl_next == (NSLOT - 1) * SLOTB) ? 0 : sl_next + SLOTB; } while (0)
;     ...
;     DMA_K(2, 2 * SLOTB);
;     WAIT_BAR(3);
;     qkt(pA0, pA1, Kbase, qr, negm, r32, hi); asm volatile("s_nop 15\n\ts_nop 7" : "+v"(pA0), "+v"(pA1));
;     START(pA0, pA1);
;     _Pragma("unroll") for (int r = 0; r < 16; ++r) pA1[r] = __builtin_amdgcn_exp2f(pA1[r]);
;     WAIT_BAR(0);
;     DMA_K(3, 0); DMA_V(1, SLOTB);
;     ROT();
;     kload8(kf, kp0 + sl_cur);
;     WAIT_BAR(2);
	s_mov_b32 s30, m0
	s_mov_b32 m0, s26
	s_nop 0
	global_load_lds_dwordx4 v193, s[38:39]
	s_mov_b32 m0, s30
	s_add_i32 s30, s26, 0x8000
	s_mov_b32 s36, m0
	s_mov_b32 m0, s30
	s_nop 0
	global_load_lds_dwordx4 v192, s[34:35]
	s_mov_b32 m0, s36
	ds_read_b128 v[98:101], v191 offset:8192
	ds_read_b128 v[170:173], v191 offset:8704
	ds_read_b128 v[174:177], v191 offset:10240
	ds_read_b128 v[166:169], v191 offset:10752
	ds_read_b128 v[142:145], v191 offset:12288
	ds_read_b128 v[138:141], v191 offset:12800
	ds_read_b128 v[134:137], v191 offset:14336
	ds_read_b128 v[130:133], v191 offset:14848
	v_exp_f32_e32 v82, v34
	v_exp_f32_e32 v83, v35
	v_exp_f32_e32 v84, v36
	v_exp_f32_e32 v85, v37
	v_exp_f32_e32 v86, v38
	v_exp_f32_e32 v87, v39
	v_exp_f32_e32 v88, v40
	v_exp_f32_e32 v89, v41
	v_exp_f32_e32 v90, v42
	v_exp_f32_e32 v91, v43
	v_exp_f32_e32 v92, v44
	v_exp_f32_e32 v93, v45
	v_exp_f32_e32 v94, v46
	v_exp_f32_e32 v95, v47
	v_exp_f32_e32 v96, v48
	v_exp_f32_e32 v97, v49
	v_exp_f32_e32 v66, v18
	v_exp_f32_e32 v67, v19
	v_exp_f32_e32 v68, v20
	v_exp_f32_e32 v69, v21
	v_exp_f32_e32 v70, v22
	v_exp_f32_e32 v71, v23
	v_exp_f32_e32 v72, v24
	v_exp_f32_e32 v73, v25
	v_exp_f32_e32 v74, v26
	v_exp_f32_e32 v75, v27
	v_exp_f32_e32 v76, v28
	v_exp_f32_e32 v77, v29
	v_exp_f32_e32 v78, v30
	v_exp_f32_e32 v79, v31
	v_exp_f32_e32 v80, v32
	v_exp_f32_e32 v81, v33
	s_waitcnt vmcnt(2) lgkmcnt(0)
	s_barrier
	v_mov_b32_e32 v18, 0
	v_mov_b32_e32 v19, v194
	v_mov_b32_e32 v20, v194
	v_mov_b32_e32 v21, v194
	v_mov_b32_e32 v22, v194
	v_mov_b32_e32 v23, v194
	v_mov_b32_e32 v24, v194
	v_mov_b32_e32 v25, v194
	v_mov_b32_e32 v26, v194
	v_mov_b32_e32 v27, v194
	v_mov_b32_e32 v28, v194
	v_mov_b32_e32 v29, v194
	v_mov_b32_e32 v30, v194
	v_mov_b32_e32 v31, v194
	v_mov_b32_e32 v32, v194
	v_mov_b32_e32 v33, v194
	v_mov_b32_e32 v34, 0
	v_mov_b32_e32 v35, v194
	v_mov_b32_e32 v36, v194
	v_mov_b32_e32 v37, v194
	v_mov_b32_e32 v38, v194
	v_mov_b32_e32 v39, v194
	v_mov_b32_e32 v40, v194
	v_mov_b32_e32 v41, v194
	v_mov_b32_e32 v42, v194
	v_mov_b32_e32 v43, v194
	v_mov_b32_e32 v44, v194
	v_mov_b32_e32 v45, v194
	v_mov_b32_e32 v46, v194
	v_mov_b32_e32 v47, v194
	v_mov_b32_e32 v48, v194
	v_mov_b32_e32 v49, v194
.LBB0_876:
	v_add_u32_e32 v195, s31, v190
	ds_read_b64_tr_b16 v[182:183], v195 offset:24576
	ds_read_b64_tr_b16 v[184:185], v195 offset:25088
	v_add_f32_e32 v2, v82, v83
	v_add_f32_e32 v2, v84, v2
	v_add_f32_e32 v2, v85, v2
	v_add_f32_e32 v2, v86, v2
	v_add_f32_e32 v2, v87, v2
	v_cvt_pk_bf16_f32 v146, v82, v83
	v_cvt_pk_bf16_f32 v147, v84, v85
	s_waitcnt lgkmcnt(9)
	v_mfma_f32_32x32x16_bf16 v[114:129], v[98:101], v[162:165], v[50:65]
	ds_read_b64_tr_b16 v[178:179], v195 offset:28672
	ds_read_b64_tr_b16 v[180:181], v195 offset:29184
	s_waitcnt lgkmcnt(10)
	v_mfma_f32_32x32x16_bf16 v[98:113], v[170:173], v[162:165], v[50:65]
	s_cmp_eq_u32 s40, 0
	s_cbranch_scc0 .Ldma_skip_a0
	s_mov_b32 s41, m0
	s_add_u32 s42, s2, s16
	s_addc_u32 s43, s22, s17
	s_add_u32 s42, s42, 0xe520300
	s_addc_u32 s43, s43, 0
	s_add_i32 m0, s29, s26
	s_nop 0
	global_load_lds_dwordx4 v193, s[42:43]
	s_add_u32 s42, s23, s16
	s_addc_u32 s43, s24, s17
	s_add_u32 s42, s42, 0xe491100
	s_addc_u32 s43, s43, 0
	s_add_i32 m0, s28, s20
	s_nop 0
	global_load_lds_dwordx4 v192, s[42:43]
	s_mov_b32 m0, s41
.Ldma_skip_a0:
	v_add_f32_e32 v2, v88, v2
	v_add_f32_e32 v2, v89, v2
	v_add_f32_e32 v2, v90, v2
	v_add_f32_e32 v2, v91, v2
	v_cvt_pk_bf16_f32 v148, v86, v87
	v_cvt_pk_bf16_f32 v149, v88, v89
	ds_read_b64_tr_b16 v[82:83], v195 offset:25600
	ds_read_b64_tr_b16 v[84:85], v195 offset:26112
	v_add_f32_e32 v2, v92, v2
	v_add_f32_e32 v2, v93, v2
	v_add_f32_e32 v2, v94, v2
	v_add_f32_e32 v2, v95, v2
	v_cvt_pk_bf16_f32 v10, v90, v91
	v_cvt_pk_bf16_f32 v11, v92, v93
	s_waitcnt lgkmcnt(11)
	v_mfma_f32_32x32x16_bf16 v[114:129], v[174:177], v[158:161], v[114:129]
	ds_read_b64_tr_b16 v[86:87], v195 offset:29696
	ds_read_b64_tr_b16 v[88:89], v195 offset:30208
	s_waitcnt lgkmcnt(12)
	v_mfma_f32_32x32x16_bf16 v[98:113], v[166:169], v[158:161], v[98:113]
	v_add_f32_e32 v2, v96, v2
	v_add_f32_e32 v2, v97, v2
	v_add_f32_e32 v2, v66, v2
	v_add_f32_e32 v2, v67, v2
	v_cvt_pk_bf16_f32 v12, v94, v95
	v_cvt_pk_bf16_f32 v13, v96, v97
	ds_read_b64_tr_b16 v[90:91], v195 offset:26624
	ds_read_b64_tr_b16 v[92:93], v195 offset:27136
	v_add_f32_e32 v2, v68, v2
	v_add_f32_e32 v2, v69, v2
	v_add_f32_e32 v2, v70, v2
	v_add_f32_e32 v2, v71, v2
	v_cvt_pk_bf16_f32 v6, v66, v67
	v_cvt_pk_bf16_f32 v7, v68, v69
	s_waitcnt lgkmcnt(13)
	v_mfma_f32_32x32x16_bf16 v[114:129], v[142:145], v[154:157], v[114:129]
	ds_read_b64_tr_b16 v[66:67], v195 offset:30720
	ds_read_b64_tr_b16 v[68:69], v195 offset:31232
	s_waitcnt lgkmcnt(14)
	v_mfma_f32_32x32x16_bf16 v[98:113], v[138:141], v[154:157], v[98:113]
	s_cmp_eq_u32 s40, 1
	s_cbranch_scc0 .Ldma_skip_a1
	s_mov_b32 s41, m0
	s_add_u32 s42, s2, s16
	s_addc_u32 s43, s22, s17
	s_add_u32 s42, s42, 0xe520300
	s_addc_u32 s43, s43, 0
	s_add_i32 m0, s29, s26
	s_nop 0
	global_load_lds_dwordx4 v193, s[42:43]
	s_add_u32 s42, s23, s16
	s_addc_u32 s43, s24, s17
	s_add_u32 s42, s42, 0xe491100
	s_addc_u32 s43, s43, 0
	s_add_i32 m0, s28, s20
	s_nop 0
	global_load_lds_dwordx4 v192, s[42:43]
	s_mov_b32 m0, s41
; #define WAIT_BAR(N) asm volatile("s_waitcnt vmcnt(" #N ") lgkmcnt(0)\n\ts_barrier" ::: "memory")
; #define RESC() do { if (resc) { asm volatile("s_waitcnt lgkmcnt(0)" ::: "memory"); \
;       _Pragma("unroll") for (int d_ = 0; d_ < 2; ++d_) _Pragma("unroll") for (int r = 0; r < 16; ++r) o[d_][r] *= wsf[crow(r, hi)]; } } while (0)
; #define ROT() do { sl_prev = sl_cur; sl_cur = sl_next; sl_next = (sl_next == (NSLOT - 1) * SLOTB) ? 0 : sl_next + SLOTB; } while (0)
;     ...
;     int t = 1;
;     for (; t + 5 < NT; t += 2) {
;         STEP(pB0, pB1, pA0, pA1, t, true, true, true);     WAIT_BAR(2); RESC(); ROT();
;         STEP(pA0, pA1, pB0, pB1, t + 1, true, true, true); WAIT_BAR(2); RESC(); ROT();
.Ldma_skip_a1:
	v_add_f32_e32 v2, v72, v2
	v_add_f32_e32 v2, v73, v2
	v_add_f32_e32 v2, v74, v2
	v_add_f32_e32 v2, v75, v2
	v_cvt_pk_bf16_f32 v8, v70, v71
	v_cvt_pk_bf16_f32 v9, v72, v73
	ds_read_b64_tr_b16 v[70:71], v195 offset:27648
	ds_read_b64_tr_b16 v[72:73], v195 offset:28160
	v_add_f32_e32 v2, v76, v2
	v_add_f32_e32 v2, v77, v2
	v_add_f32_e32 v2, v78, v2
	v_add_f32_e32 v94, v79, v2
	v_cvt_pk_bf16_f32 v2, v74, v75
	v_cvt_pk_bf16_f32 v3, v76, v77
	s_waitcnt lgkmcnt(14)
	v_mfma_f32_32x32x16_bf16 v[114:129], v[134:137], v[150:153], v[114:129]
	ds_read_b64_tr_b16 v[74:75], v195 offset:31744
	ds_read_b64_tr_b16 v[76:77], v195 offset:32256
	v_mfma_f32_32x32x16_bf16 v[98:113], v[130:133], v[150:153], v[98:113]
	v_add_f32_e32 v4, v80, v94
	v_add_f32_e32 v4, v81, v4
	v_add_f32_e32 v195, 0, v4
	v_cvt_pk_bf16_f32 v4, v78, v79
	v_cvt_pk_bf16_f32 v5, v80, v81
	s_waitcnt lgkmcnt(14)
	v_mfma_f32_32x32x16_bf16 v[18:33], v[146:149], v[182:185], v[18:33]
	v_exp_f32_e32 v114, v114
	v_exp_f32_e32 v115, v115
	v_exp_f32_e32 v116, v116
	v_exp_f32_e32 v117, v117
	s_waitcnt lgkmcnt(12)
	v_mfma_f32_32x32x16_bf16 v[34:49], v[146:149], v[178:181], v[34:49]
	s_cmp_eq_u32 s40, 2
	s_cbranch_scc0 .Ldma_skip_a2
	s_mov_b32 s41, m0
	s_add_u32 s42, s2, s16
	s_addc_u32 s43, s22, s17
	s_add_u32 s42, s42, 0xe520300
	s_addc_u32 s43, s43, 0
	s_add_i32 m0, s29, s26
	s_nop 0
	global_load_lds_dwordx4 v193, s[42:43]
	s_add_u32 s42, s23, s16
	s_addc_u32 s43, s24, s17
	s_add_u32 s42, s42, 0xe491100
	s_addc_u32 s43, s43, 0
	s_add_i32 m0, s28, s20
	s_nop 0
	global_load_lds_dwordx4 v192, s[42:43]
	s_mov_b32 m0, s41
.Ldma_skip_a2:
	v_exp_f32_e32 v118, v118
	v_exp_f32_e32 v119, v119
	v_exp_f32_e32 v120, v120
	v_exp_f32_e32 v121, v121
	v_add_u32_e32 v94, s28, v191
	ds_read_b128 v[78:81], v94
	ds_read_b128 v[134:137], v94 offset:512
	s_waitcnt lgkmcnt(12)
	v_mfma_f32_32x32x16_bf16 v[18:33], v[10:13], v[82:85], v[18:33]
	v_exp_f32_e32 v122, v122
	v_exp_f32_e32 v123, v123
	v_exp_f32_e32 v124, v124
	v_exp_f32_e32 v125, v125
	ds_read_b128 v[138:141], v94 offset:2048
	ds_read_b128 v[142:145], v94 offset:2560
	s_waitcnt lgkmcnt(12)
	v_mfma_f32_32x32x16_bf16 v[34:49], v[10:13], v[86:89], v[34:49]
	v_exp_f32_e32 v126, v126
	v_exp_f32_e32 v127, v127
	v_exp_f32_e32 v128, v128
	v_exp_f32_e32 v129, v129
	ds_read_b128 v[166:169], v94 offset:4096
	ds_read_b128 v[170:173], v94 offset:4608
	s_waitcnt lgkmcnt(12)
	v_mfma_f32_32x32x16_bf16 v[18:33], v[6:9], v[90:93], v[18:33]
	v_exp_f32_e32 v98, v98
	v_exp_f32_e32 v99, v99
	v_exp_f32_e32 v100, v100
	v_exp_f32_e32 v101, v101
	ds_read_b128 v[174:177], v94 offset:6144
	ds_read_b128 v[130:133], v94 offset:6656
	s_waitcnt lgkmcnt(12)
	v_mfma_f32_32x32x16_bf16 v[34:49], v[6:9], v[66:69], v[34:49]
	s_cmp_eq_u32 s40, 3
	s_cbranch_scc0 .Ldma_skip_a3
	s_mov_b32 s41, m0
	s_add_u32 s42, s2, s16
	s_addc_u32 s43, s22, s17
	s_add_u32 s42, s42, 0xe520300
	s_addc_u32 s43, s43, 0
	s_add_i32 m0, s29, s26
	s_nop 0
	global_load_lds_dwordx4 v193, s[42:43]
	s_add_u32 s42, s23, s16
	s_addc_u32 s43, s24, s17
	s_add_u32 s42, s42, 0xe491100
	s_addc_u32 s43, s43, 0
	s_add_i32 m0, s28, s20
	s_nop 0
	global_load_lds_dwordx4 v192, s[42:43]
	s_mov_b32 m0, s41
.Ldma_skip_a3:
	v_exp_f32_e32 v102, v102
	v_exp_f32_e32 v103, v103
	v_exp_f32_e32 v104, v104
	v_exp_f32_e32 v105, v105
	s_waitcnt lgkmcnt(10)
	v_mfma_f32_32x32x16_bf16 v[18:33], v[2:5], v[70:73], v[18:33]
	v_exp_f32_e32 v106, v106
	v_exp_f32_e32 v107, v107
	v_exp_f32_e32 v108, v108
	v_exp_f32_e32 v109, v109
	s_waitcnt lgkmcnt(8)
	v_mfma_f32_32x32x16_bf16 v[34:49], v[2:5], v[74:77], v[34:49]
	v_exp_f32_e32 v110, v110
	v_exp_f32_e32 v111, v111
	v_exp_f32_e32 v112, v112
	v_exp_f32_e32 v113, v113
	s_waitcnt vmcnt(2) lgkmcnt(0)
	s_barrier
	s_add_i32 s30, s28, 0x2000
	s_cmpk_lg_i32 s28, 0x4000
	s_cselect_b32 s30, s30, 0
	v_add_u32_e32 v196, s29, v190
	ds_read_b64_tr_b16 v[178:179], v196 offset:24576
	ds_read_b64_tr_b16 v[180:181], v196 offset:25088
	s_waitcnt lgkmcnt(9)
	v_mfma_f32_32x32x16_bf16 v[82:97], v[78:81], v[162:165], v[50:65]
	v_add_f32_e32 v2, v114, v115
	v_add_f32_e32 v2, v116, v2
	v_add_f32_e32 v2, v117, v2
	v_add_f32_e32 v2, v118, v2
	v_add_f32_e32 v2, v119, v2
	v_cvt_pk_bf16_f32 v146, v114, v115
	v_cvt_pk_bf16_f32 v147, v116, v117
	ds_read_b64_tr_b16 v[182:183], v196 offset:28672
	ds_read_b64_tr_b16 v[184:185], v196 offset:29184
	s_waitcnt lgkmcnt(10)
	v_mfma_f32_32x32x16_bf16 v[66:81], v[134:137], v[162:165], v[50:65]
	s_cmp_eq_u32 s40, 0
	s_cbranch_scc0 .Ldma_skip_b0
	s_mov_b32 s41, m0
	s_add_u32 s42, s2, s16
	s_addc_u32 s43, s22, s17
	s_add_u32 s42, s42, 0xe568300
	s_addc_u32 s43, s43, 0
	s_add_i32 m0, s28, s26
	s_nop 0
	global_load_lds_dwordx4 v193, s[42:43]
	s_add_u32 s42, s23, s16
	s_addc_u32 s43, s24, s17
	s_add_u32 s42, s42, 0xe4d9100
	s_addc_u32 s43, s43, 0
	s_add_i32 m0, s30, s20
	s_nop 0
	global_load_lds_dwordx4 v192, s[42:43]
	s_mov_b32 m0, s41
; #define WAIT_BAR(N) asm volatile("s_waitcnt vmcnt(" #N ") lgkmcnt(0)\n\ts_barrier" ::: "memory")
; #define RESC() do { if (resc) { asm volatile("s_waitcnt lgkmcnt(0)" ::: "memory"); \
;       _Pragma("unroll") for (int d_ = 0; d_ < 2; ++d_) _Pragma("unroll") for (int r = 0; r < 16; ++r) o[d_][r] *= wsf[crow(r, hi)]; } } while (0)
; #define ROT() do { sl_prev = sl_cur; sl_cur = sl_next; sl_next = (sl_next == (NSLOT - 1) * SLOTB) ? 0 : sl_next + SLOTB; } while (0)
;     ...
;     int t = 1;
;     for (; t + 5 < NT; t += 2) {
;         STEP(pB0, pB1, pA0, pA1, t, true, true, true);     WAIT_BAR(2); RESC(); ROT();
;         STEP(pA0, pA1, pB0, pB1, t + 1, true, true, true); WAIT_BAR(2); RESC(); ROT();
.Ldma_skip_b0:
	v_add_f32_e32 v2, v120, v2
	v_add_f32_e32 v2, v121, v2
	v_add_f32_e32 v2, v122, v2
	v_add_f32_e32 v2, v123, v2
	v_cvt_pk_bf16_f32 v148, v118, v119
	v_cvt_pk_bf16_f32 v149, v120, v121
	ds_read_b64_tr_b16 v[114:115], v196 offset:25600
	ds_read_b64_tr_b16 v[116:117], v196 offset:26112
	s_waitcnt lgkmcnt(11)
	v_mfma_f32_32x32x16_bf16 v[82:97], v[138:141], v[158:161], v[82:97]
	v_add_f32_e32 v2, v124, v2
	v_add_f32_e32 v2, v125, v2
	v_add_f32_e32 v2, v126, v2
	v_add_f32_e32 v2, v127, v2
	v_cvt_pk_bf16_f32 v10, v122, v123
	v_cvt_pk_bf16_f32 v11, v124, v125
	ds_read_b64_tr_b16 v[118:119], v196 offset:29696
	ds_read_b64_tr_b16 v[120:121], v196 offset:30208
	s_waitcnt lgkmcnt(12)
	v_mfma_f32_32x32x16_bf16 v[66:81], v[142:145], v[158:161], v[66:81]
	v_add_f32_e32 v2, v128, v2
	v_add_f32_e32 v2, v129, v2
	v_add_f32_e32 v2, v98, v2
	v_add_f32_e32 v2, v99, v2
	v_cvt_pk_bf16_f32 v12, v126, v127
	v_cvt_pk_bf16_f32 v13, v128, v129
	ds_read_b64_tr_b16 v[122:123], v196 offset:26624
	ds_read_b64_tr_b16 v[124:125], v196 offset:27136
	s_waitcnt lgkmcnt(13)
	v_mfma_f32_32x32x16_bf16 v[82:97], v[166:169], v[154:157], v[82:97]
	v_add_f32_e32 v2, v100, v2
	v_add_f32_e32 v2, v101, v2
	v_add_f32_e32 v2, v102, v2
	v_add_f32_e32 v2, v103, v2
	v_cvt_pk_bf16_f32 v6, v98, v99
	v_cvt_pk_bf16_f32 v7, v100, v101
	ds_read_b64_tr_b16 v[126:127], v196 offset:30720
	ds_read_b64_tr_b16 v[128:129], v196 offset:31232
	s_waitcnt lgkmcnt(14)
	v_mfma_f32_32x32x16_bf16 v[66:81], v[170:173], v[154:157], v[66:81]
	s_cmp_eq_u32 s40, 1
	s_cbranch_scc0 .Ldma_skip_b1
	s_mov_b32 s41, m0
	s_add_u32 s42, s2, s16
	s_addc_u32 s43, s22, s17
	s_add_u32 s42, s42, 0xe568300
	s_addc_u32 s43, s43, 0
	s_add_i32 m0, s28, s26
	s_nop 0
	global_load_lds_dwordx4 v193, s[42:43]
	s_add_u32 s42, s23, s16
	s_addc_u32 s43, s24, s17
	s_add_u32 s42, s42, 0xe4d9100
	s_addc_u32 s43, s43, 0
	s_add_i32 m0, s30, s20
	s_nop 0
	global_load_lds_dwordx4 v192, s[42:43]
	s_mov_b32 m0, s41
.Ldma_skip_b1:
	v_add_f32_e32 v2, v104, v2
	v_add_f32_e32 v2, v105, v2
	v_add_f32_e32 v2, v106, v2
	v_add_f32_e32 v2, v107, v2
	v_cvt_pk_bf16_f32 v8, v102, v103
	v_cvt_pk_bf16_f32 v9, v104, v105
	ds_read_b64_tr_b16 v[102:103], v196 offset:27648
	ds_read_b64_tr_b16 v[104:105], v196 offset:28160
	s_waitcnt lgkmcnt(14)
	v_mfma_f32_32x32x16_bf16 v[82:97], v[174:177], v[150:153], v[82:97]
	v_add_f32_e32 v2, v108, v2
	v_add_f32_e32 v2, v109, v2
	v_add_f32_e32 v2, v110, v2
	v_add_f32_e32 v98, v111, v2
	v_cvt_pk_bf16_f32 v2, v106, v107
	v_cvt_pk_bf16_f32 v3, v108, v109
	ds_read_b64_tr_b16 v[106:107], v196 offset:31744
	ds_read_b64_tr_b16 v[108:109], v196 offset:32256
	v_mfma_f32_32x32x16_bf16 v[66:81], v[130:133], v[150:153], v[66:81]
	v_add_f32_e32 v4, v112, v98
	v_add_f32_e32 v4, v113, v4
	v_add_f32_e32 v196, 0, v4
	v_cvt_pk_bf16_f32 v4, v110, v111
	v_cvt_pk_bf16_f32 v5, v112, v113
	s_waitcnt lgkmcnt(14)
	v_mfma_f32_32x32x16_bf16 v[18:33], v[146:149], v[178:181], v[18:33]
	v_exp_f32_e32 v82, v82
	v_exp_f32_e32 v83, v83
	v_exp_f32_e32 v84, v84
	v_exp_f32_e32 v85, v85
	s_waitcnt lgkmcnt(12)
	v_mfma_f32_32x32x16_bf16 v[34:49], v[146:149], v[182:185], v[34:49]
	s_cmp_eq_u32 s40, 2
	s_cbranch_scc0 .Ldma_skip_b2
	s_mov_b32 s41, m0
	s_add_u32 s42, s2, s16
	s_addc_u32 s43, s22, s17
	s_add_u32 s42, s42, 0xe568300
	s_addc_u32 s43, s43, 0
	s_add_i32 m0, s28, s26
	s_nop 0
	global_load_lds_dwordx4 v193, s[42:43]
	s_add_u32 s42, s23, s16
	s_addc_u32 s43, s24, s17
	s_add_u32 s42, s42, 0xe4d9100
	s_addc_u32 s43, s43, 0
	s_add_i32 m0, s30, s20
	s_nop 0
	global_load_lds_dwordx4 v192, s[42:43]
	s_mov_b32 m0, s41
.Ldma_skip_b2:
	v_exp_f32_e32 v86, v86
	v_exp_f32_e32 v87, v87
	v_exp_f32_e32 v88, v88
	v_exp_f32_e32 v89, v89
	v_add_u32_e32 v110, s30, v191
	ds_read_b128 v[98:101], v110
	ds_read_b128 v[170:173], v110 offset:512
	s_waitcnt lgkmcnt(12)
	v_mfma_f32_32x32x16_bf16 v[18:33], v[10:13], v[114:117], v[18:33]
	v_exp_f32_e32 v90, v90
	v_exp_f32_e32 v91, v91
	v_exp_f32_e32 v92, v92
	v_exp_f32_e32 v93, v93
	ds_read_b128 v[174:177], v110 offset:2048
	ds_read_b128 v[166:169], v110 offset:2560
	s_waitcnt lgkmcnt(12)
	v_mfma_f32_32x32x16_bf16 v[34:49], v[10:13], v[118:121], v[34:49]
	v_exp_f32_e32 v94, v94
	v_exp_f32_e32 v95, v95
	v_exp_f32_e32 v96, v96
	v_exp_f32_e32 v97, v97
	ds_read_b128 v[142:145], v110 offset:4096
	ds_read_b128 v[138:141], v110 offset:4608
	s_waitcnt lgkmcnt(12)
	v_mfma_f32_32x32x16_bf16 v[18:33], v[6:9], v[122:125], v[18:33]
	v_exp_f32_e32 v66, v66
	v_exp_f32_e32 v67, v67
	v_exp_f32_e32 v68, v68
	v_exp_f32_e32 v69, v69
	ds_read_b128 v[134:137], v110 offset:6144
	ds_read_b128 v[130:133], v110 offset:6656
	s_waitcnt lgkmcnt(12)
	v_mfma_f32_32x32x16_bf16 v[34:49], v[6:9], v[126:129], v[34:49]
	s_cmp_eq_u32 s40, 3
	s_cbranch_scc0 .Ldma_skip_b3
	s_mov_b32 s41, m0
	s_add_u32 s42, s2, s16
	s_addc_u32 s43, s22, s17
	s_add_u32 s42, s42, 0xe568300
	s_addc_u32 s43, s43, 0
	s_add_i32 m0, s28, s26
	s_nop 0
	global_load_lds_dwordx4 v193, s[42:43]
	s_add_u32 s42, s23, s16
	s_addc_u32 s43, s24, s17
	s_add_u32 s42, s42, 0xe4d9100
	s_addc_u32 s43, s43, 0
	s_add_i32 m0, s30, s20
	s_nop 0
	global_load_lds_dwordx4 v192, s[42:43]
	s_mov_b32 m0, s41
; #define WAIT_BAR(N) asm volatile("s_waitcnt vmcnt(" #N ") lgkmcnt(0)\n\ts_barrier" ::: "memory")
; #define RESC() do { if (resc) { asm volatile("s_waitcnt lgkmcnt(0)" ::: "memory"); \
;       _Pragma("unroll") for (int d_ = 0; d_ < 2; ++d_) _Pragma("unroll") for (int r = 0; r < 16; ++r) o[d_][r] *= wsf[crow(r, hi)]; } } while (0)
; #define ROT() do { sl_prev = sl_cur; sl_cur = sl_next; sl_next = (sl_next == (NSLOT - 1) * SLOTB) ? 0 : sl_next + SLOTB; } while (0)
; #define ENDW(tt) do { if ((tt) + 3 < NT) { WAIT_BAR(2); } else if ((tt) + 2 < NT) { WAIT_BAR(1); } else { WAIT_BAR(0); } } while (0)
;     ...
;     int t = 1;
;     for (; t + 5 < NT; t += 2) {
;         STEP(pB0, pB1, pA0, pA1, t, true, true, true);     WAIT_BAR(2); RESC(); ROT();
;         STEP(pA0, pA1, pB0, pB1, t + 1, true, true, true); WAIT_BAR(2); RESC(); ROT();
;     }
;     ...
;     for (; t + 1 < NT; t += 2) {
;         STEP(pB0, pB1, pA0, pA1, t, (t + 3 < NT), (t + 1 < NT), (t + 1 < NT));         ENDW(t);     RESC(); ROT();
;         STEP(pA0, pA1, pB0, pB1, t + 1, (t + 4 < NT), (t + 2 < NT), (t + 2 < NT));     ENDW(t + 1); RESC(); ROT();
;     }
.Ldma_skip_b3:
	v_exp_f32_e32 v70, v70
	v_exp_f32_e32 v71, v71
	v_exp_f32_e32 v72, v72
	v_exp_f32_e32 v73, v73
	s_waitcnt lgkmcnt(10)
	v_mfma_f32_32x32x16_bf16 v[18:33], v[2:5], v[102:105], v[18:33]
	v_exp_f32_e32 v74, v74
	v_exp_f32_e32 v75, v75
	v_exp_f32_e32 v76, v76
	v_exp_f32_e32 v77, v77
	s_waitcnt lgkmcnt(8)
	v_mfma_f32_32x32x16_bf16 v[34:49], v[2:5], v[106:109], v[34:49]
	v_exp_f32_e32 v78, v78
	v_exp_f32_e32 v79, v79
	v_exp_f32_e32 v80, v80
	v_exp_f32_e32 v81, v81
	s_add_i32 s34, s30, 0x2000
	s_cmpk_lg_i32 s30, 0x4000
	s_mov_b32 s31, s28
	s_cselect_b32 s28, s34, 0
	s_add_i32 s27, s27, 2
	s_add_u32 s23, s23, 0x90000
	s_addc_u32 s24, s24, 0
	s_waitcnt vmcnt(2) lgkmcnt(0)
	s_barrier
	s_add_u32 s2, s2, 0x90000
	v_add_f32_e32 v2, v194, v195
	s_addc_u32 s22, s22, 0
	s_mov_b32 s29, s30
	v_add_f32_e32 v194, v2, v196
	s_cmpk_gt_u32 s27, 0x7c
	s_cbranch_scc0 .LBB0_876
	s_and_b32 s2, s25, 0x3fffffc0
	s_lshl_b32 s2, s2, 2
	s_add_i32 s2, s2, 0
	ds_read_b64_tr_b16 v[182:183], v190 offset:24576
	ds_read_b64_tr_b16 v[184:185], v190 offset:25088
	v_add_f32_e32 v2, v82, v83
	v_add_f32_e32 v2, v84, v2
	v_add_f32_e32 v2, v85, v2
	v_add_f32_e32 v2, v86, v2
	v_add_f32_e32 v2, v87, v2
	v_cvt_pk_bf16_f32 v146, v82, v83
	v_cvt_pk_bf16_f32 v147, v84, v85
	s_waitcnt lgkmcnt(9)
	v_mfma_f32_32x32x16_bf16 v[114:129], v[98:101], v[162:165], v[50:65]
	ds_read_b64_tr_b16 v[178:179], v190 offset:28672
	ds_read_b64_tr_b16 v[180:181], v190 offset:29184
	v_add_f32_e32 v2, v88, v2
	v_add_f32_e32 v2, v89, v2
	v_add_f32_e32 v2, v90, v2
	v_add_f32_e32 v2, v91, v2
	v_cvt_pk_bf16_f32 v148, v86, v87
	v_cvt_pk_bf16_f32 v149, v88, v89
	s_waitcnt lgkmcnt(10)
	v_mfma_f32_32x32x16_bf16 v[98:113], v[170:173], v[162:165], v[50:65]
	ds_read_b64_tr_b16 v[82:83], v190 offset:25600
	ds_read_b64_tr_b16 v[84:85], v190 offset:26112
	v_add_f32_e32 v2, v92, v2
	v_add_f32_e32 v2, v93, v2
	v_add_f32_e32 v2, v94, v2
	v_add_f32_e32 v2, v95, v2
	v_cvt_pk_bf16_f32 v10, v90, v91
	v_cvt_pk_bf16_f32 v11, v92, v93
	s_waitcnt lgkmcnt(11)
	v_mfma_f32_32x32x16_bf16 v[114:129], v[174:177], v[158:161], v[114:129]
	ds_read_b64_tr_b16 v[86:87], v190 offset:29696
	ds_read_b64_tr_b16 v[88:89], v190 offset:30208
	v_add_f32_e32 v2, v96, v2
	v_add_f32_e32 v2, v97, v2
	v_add_f32_e32 v2, v66, v2
	v_add_f32_e32 v2, v67, v2
	v_cvt_pk_bf16_f32 v12, v94, v95
	v_cvt_pk_bf16_f32 v13, v96, v97
	s_waitcnt lgkmcnt(12)
	v_mfma_f32_32x32x16_bf16 v[98:113], v[166:169], v[158:161], v[98:113]
	ds_read_b64_tr_b16 v[90:91], v190 offset:26624
	ds_read_b64_tr_b16 v[92:93], v190 offset:27136
	v_add_f32_e32 v2, v68, v2
	v_add_f32_e32 v2, v69, v2
	v_add_f32_e32 v2, v70, v2
	v_add_f32_e32 v2, v71, v2
	v_cvt_pk_bf16_f32 v6, v66, v67
	v_cvt_pk_bf16_f32 v7, v68, v69
	s_waitcnt lgkmcnt(13)
	v_mfma_f32_32x32x16_bf16 v[114:129], v[142:145], v[154:157], v[114:129]
	ds_read_b64_tr_b16 v[66:67], v190 offset:30720
	ds_read_b64_tr_b16 v[68:69], v190 offset:31232
	v_add_f32_e32 v2, v72, v2
	v_add_f32_e32 v2, v73, v2
	v_add_f32_e32 v2, v74, v2
	v_add_f32_e32 v2, v75, v2
	v_cvt_pk_bf16_f32 v8, v70, v71
	v_cvt_pk_bf16_f32 v9, v72, v73
	s_waitcnt lgkmcnt(14)
	v_mfma_f32_32x32x16_bf16 v[98:113], v[138:141], v[154:157], v[98:113]
	ds_read_b64_tr_b16 v[70:71], v190 offset:27648
	ds_read_b64_tr_b16 v[72:73], v190 offset:28160
	v_add_f32_e32 v2, v76, v2
	v_add_f32_e32 v2, v77, v2
	v_add_f32_e32 v2, v78, v2
	v_add_f32_e32 v94, v79, v2
	v_cvt_pk_bf16_f32 v2, v74, v75
	v_cvt_pk_bf16_f32 v3, v76, v77
	s_waitcnt lgkmcnt(14)
	v_mfma_f32_32x32x16_bf16 v[114:129], v[134:137], v[150:153], v[114:129]
	ds_read_b64_tr_b16 v[74:75], v190 offset:31744
	ds_read_b64_tr_b16 v[76:77], v190 offset:32256
	v_add_f32_e32 v4, v80, v94
	v_add_f32_e32 v4, v81, v4
	v_add_f32_e32 v94, 0, v4
	v_cvt_pk_bf16_f32 v4, v78, v79
	v_cvt_pk_bf16_f32 v5, v80, v81
	v_mfma_f32_32x32x16_bf16 v[98:113], v[130:133], v[150:153], v[98:113]
	s_add_u32 s16, s14, 0x2490000
	s_addc_u32 s17, s15, 0
	s_cmp_lg_u32 0, -1
	s_cselect_b32 s23, 0, 0
	s_add_i32 s22, s23, s21
	s_add_i32 s24, s22, 0x2000
	s_mov_b32 s25, m0
	s_mov_b32 m0, s24
	s_nop 0
	global_load_lds_dwordx4 v193, s[16:17]
	s_mov_b32 m0, s25
	s_add_u32 s24, s12, 0x2400000
	s_addc_u32 s25, s13, 0
	s_add_i32 s16, s23, 0xa000
	s_add_i32 s17, s21, s16
	s_mov_b32 s21, m0
	s_mov_b32 m0, s17
	s_nop 0
	global_load_lds_dwordx4 v192, s[24:25]
	s_mov_b32 m0, s21
	v_add_f32_e32 v194, v194, v94
	s_waitcnt lgkmcnt(14)
	v_mfma_f32_32x32x16_bf16 v[18:33], v[146:149], v[182:185], v[18:33]
	v_exp_f32_e32 v114, v114
	v_exp_f32_e32 v115, v115
	v_exp_f32_e32 v116, v116
	v_exp_f32_e32 v117, v117
	s_waitcnt lgkmcnt(12)
	v_mfma_f32_32x32x16_bf16 v[34:49], v[146:149], v[178:181], v[34:49]
	v_exp_f32_e32 v118, v118
	v_exp_f32_e32 v119, v119
	v_exp_f32_e32 v120, v120
	v_exp_f32_e32 v121, v121
	ds_read_b128 v[78:81], v191 offset:16384
	ds_read_b128 v[94:97], v191 offset:16896
	s_waitcnt lgkmcnt(12)
	v_mfma_f32_32x32x16_bf16 v[18:33], v[10:13], v[82:85], v[18:33]
	v_exp_f32_e32 v122, v122
	v_exp_f32_e32 v123, v123
	v_exp_f32_e32 v124, v124
	v_exp_f32_e32 v125, v125
	ds_read_b128 v[166:169], v191 offset:18432
	ds_read_b128 v[170:173], v191 offset:18944
	s_waitcnt lgkmcnt(12)
	v_mfma_f32_32x32x16_bf16 v[34:49], v[10:13], v[86:89], v[34:49]
	v_exp_f32_e32 v126, v126
	v_exp_f32_e32 v127, v127
	v_exp_f32_e32 v128, v128
	v_exp_f32_e32 v129, v129
	ds_read_b128 v[174:177], v191 offset:20480
	ds_read_b128 v[178:181], v191 offset:20992
	s_waitcnt lgkmcnt(12)
	v_mfma_f32_32x32x16_bf16 v[18:33], v[6:9], v[90:93], v[18:33]
	v_exp_f32_e32 v98, v98
	v_exp_f32_e32 v99, v99
	v_exp_f32_e32 v100, v100
	v_exp_f32_e32 v101, v101
	ds_read_b128 v[90:93], v191 offset:22528
	ds_read_b128 v[82:85], v191 offset:23040
	s_waitcnt lgkmcnt(12)
	v_mfma_f32_32x32x16_bf16 v[34:49], v[6:9], v[66:69], v[34:49]
	v_exp_f32_e32 v102, v102
	v_exp_f32_e32 v103, v103
	v_exp_f32_e32 v104, v104
	v_exp_f32_e32 v105, v105
	s_waitcnt lgkmcnt(10)
	v_mfma_f32_32x32x16_bf16 v[18:33], v[2:5], v[70:73], v[18:33]
	v_exp_f32_e32 v106, v106
	v_exp_f32_e32 v107, v107
	v_exp_f32_e32 v108, v108
	v_exp_f32_e32 v109, v109
	s_waitcnt lgkmcnt(8)
	v_mfma_f32_32x32x16_bf16 v[34:49], v[2:5], v[74:77], v[34:49]
	v_exp_f32_e32 v110, v110
	v_exp_f32_e32 v111, v111
	v_exp_f32_e32 v112, v112
	v_exp_f32_e32 v113, v113
	s_waitcnt vmcnt(2) lgkmcnt(0)
	s_barrier
; #define WAIT_BAR(N) asm volatile("s_waitcnt vmcnt(" #N ") lgkmcnt(0)\n\ts_barrier" ::: "memory")
; #define RESC() do { if (resc) { asm volatile("s_waitcnt lgkmcnt(0)" ::: "memory"); \
;       _Pragma("unroll") for (int d_ = 0; d_ < 2; ++d_) _Pragma("unroll") for (int r = 0; r < 16; ++r) o[d_][r] *= wsf[crow(r, hi)]; } } while (0)
; #define ROT() do { sl_prev = sl_cur; sl_cur = sl_next; sl_next = (sl_next == (NSLOT - 1) * SLOTB) ? 0 : sl_next + SLOTB; } while (0)
; #define ENDW(tt) do { if ((tt) + 3 < NT) { WAIT_BAR(2); } else if ((tt) + 2 < NT) { WAIT_BAR(1); } else { WAIT_BAR(0); } } while (0)
;     ...
;     int t = 1;
;     for (; t + 5 < NT; t += 2) {
;         STEP(pB0, pB1, pA0, pA1, t, true, true, true);     WAIT_BAR(2); RESC(); ROT();
;         STEP(pA0, pA1, pB0, pB1, t + 1, true, true, true); WAIT_BAR(2); RESC(); ROT();
;     }
;     ...
;     for (; t + 1 < NT; t += 2) {
;         STEP(pB0, pB1, pA0, pA1, t, (t + 3 < NT), (t + 1 < NT), (t + 1 < NT));         ENDW(t);     RESC(); ROT();
;         STEP(pA0, pA1, pB0, pB1, t + 1, (t + 4 < NT), (t + 2 < NT), (t + 2 < NT));     ENDW(t + 1); RESC(); ROT();
	ds_read_b64_tr_b16 v[182:183], v190 offset:32768
	ds_read_b64_tr_b16 v[184:185], v190 offset:33280
	v_add_f32_e32 v2, v114, v115
	v_add_f32_e32 v2, v116, v2
	v_add_f32_e32 v2, v117, v2
	v_add_f32_e32 v2, v118, v2
	v_add_f32_e32 v2, v119, v2
	v_cvt_pk_bf16_f32 v146, v114, v115
	v_cvt_pk_bf16_f32 v147, v116, v117
	s_waitcnt lgkmcnt(9)
	v_mfma_f32_32x32x16_bf16 v[130:145], v[78:81], v[162:165], v[50:65]
	ds_read_b64_tr_b16 v[114:115], v190 offset:36864
	ds_read_b64_tr_b16 v[116:117], v190 offset:37376
	s_waitcnt lgkmcnt(10)
	v_mfma_f32_32x32x16_bf16 v[66:81], v[94:97], v[162:165], v[50:65]
	v_add_f32_e32 v2, v120, v2
	v_add_f32_e32 v2, v121, v2
	v_add_f32_e32 v2, v122, v2
	v_add_f32_e32 v2, v123, v2
	v_cvt_pk_bf16_f32 v148, v118, v119
	v_cvt_pk_bf16_f32 v149, v120, v121
	ds_read_b64_tr_b16 v[86:87], v190 offset:33792
	ds_read_b64_tr_b16 v[88:89], v190 offset:34304
	v_add_f32_e32 v2, v124, v2
	v_add_f32_e32 v2, v125, v2
	v_add_f32_e32 v2, v126, v2
	v_add_f32_e32 v2, v127, v2
	v_cvt_pk_bf16_f32 v10, v122, v123
	v_cvt_pk_bf16_f32 v11, v124, v125
	s_waitcnt lgkmcnt(11)
	v_mfma_f32_32x32x16_bf16 v[130:145], v[166:169], v[158:161], v[130:145]
	ds_read_b64_tr_b16 v[94:95], v190 offset:37888
	ds_read_b64_tr_b16 v[96:97], v190 offset:38400
	s_waitcnt lgkmcnt(12)
	v_mfma_f32_32x32x16_bf16 v[66:81], v[170:173], v[158:161], v[66:81]
	v_add_f32_e32 v2, v128, v2
	v_add_f32_e32 v2, v129, v2
	v_add_f32_e32 v2, v98, v2
	v_add_f32_e32 v2, v99, v2
	v_cvt_pk_bf16_f32 v12, v126, v127
	v_cvt_pk_bf16_f32 v13, v128, v129
	ds_read_b64_tr_b16 v[118:119], v190 offset:34816
	ds_read_b64_tr_b16 v[120:121], v190 offset:35328
	v_add_f32_e32 v2, v100, v2
	v_add_f32_e32 v2, v101, v2
	v_add_f32_e32 v2, v102, v2
	v_add_f32_e32 v2, v103, v2
	v_cvt_pk_bf16_f32 v6, v98, v99
	v_cvt_pk_bf16_f32 v7, v100, v101
	s_waitcnt lgkmcnt(13)
	v_mfma_f32_32x32x16_bf16 v[130:145], v[174:177], v[154:157], v[130:145]
	ds_read_b64_tr_b16 v[122:123], v190 offset:38912
	ds_read_b64_tr_b16 v[124:125], v190 offset:39424
	s_waitcnt lgkmcnt(14)
	v_mfma_f32_32x32x16_bf16 v[66:81], v[178:181], v[154:157], v[66:81]
	v_add_f32_e32 v2, v104, v2
	v_add_f32_e32 v2, v105, v2
	v_add_f32_e32 v2, v106, v2
	v_add_f32_e32 v2, v107, v2
	v_cvt_pk_bf16_f32 v8, v102, v103
	v_cvt_pk_bf16_f32 v9, v104, v105
	ds_read_b64_tr_b16 v[102:103], v190 offset:35840
	ds_read_b64_tr_b16 v[104:105], v190 offset:36352
	v_add_f32_e32 v2, v108, v2
	v_add_f32_e32 v2, v109, v2
	v_add_f32_e32 v2, v110, v2
	v_add_f32_e32 v98, v111, v2
	v_cvt_pk_bf16_f32 v2, v106, v107
	v_cvt_pk_bf16_f32 v3, v108, v109
	s_waitcnt lgkmcnt(14)
	v_mfma_f32_32x32x16_bf16 v[130:145], v[90:93], v[150:153], v[130:145]
	ds_read_b64_tr_b16 v[90:91], v190 offset:39936
	ds_read_b64_tr_b16 v[92:93], v190 offset:40448
	v_mfma_f32_32x32x16_bf16 v[66:81], v[82:85], v[150:153], v[66:81]
	v_add_f32_e32 v4, v112, v98
	v_add_f32_e32 v4, v113, v4
	v_add_f32_e32 v82, 0, v4
	v_cvt_pk_bf16_f32 v4, v110, v111
	v_cvt_pk_bf16_f32 v5, v112, v113
	s_add_u32 s14, s14, 0x24d8000
	s_addc_u32 s15, s15, 0
	s_add_i32 s21, s22, 0x4000
	s_mov_b32 s23, m0
	s_mov_b32 m0, s21
	s_nop 0
	global_load_lds_dwordx4 v193, s[14:15]
	s_mov_b32 m0, s23
	s_add_u32 s14, s12, 0x2448000
	s_addc_u32 s15, s13, 0
	s_mov_b32 s21, m0
	s_mov_b32 m0, s20
	s_nop 0
	global_load_lds_dwordx4 v192, s[14:15]
	s_mov_b32 m0, s21
	v_add_f32_e32 v194, v194, v82
	s_waitcnt lgkmcnt(14)
	v_mfma_f32_32x32x16_bf16 v[18:33], v[146:149], v[182:185], v[18:33]
	v_exp_f32_e32 v130, v130
	v_exp_f32_e32 v131, v131
	v_exp_f32_e32 v132, v132
	v_exp_f32_e32 v133, v133
	s_waitcnt lgkmcnt(12)
	v_mfma_f32_32x32x16_bf16 v[34:49], v[146:149], v[114:117], v[34:49]
	v_exp_f32_e32 v134, v134
	v_exp_f32_e32 v135, v135
	v_exp_f32_e32 v136, v136
	v_exp_f32_e32 v137, v137
	ds_read_b128 v[82:85], v191
	ds_read_b128 v[106:109], v191 offset:512
	s_waitcnt lgkmcnt(12)
	v_mfma_f32_32x32x16_bf16 v[18:33], v[10:13], v[86:89], v[18:33]
	v_exp_f32_e32 v138, v138
	v_exp_f32_e32 v139, v139
	v_exp_f32_e32 v140, v140
	v_exp_f32_e32 v141, v141
	ds_read_b128 v[110:113], v191 offset:2048
	ds_read_b128 v[166:169], v191 offset:2560
	s_waitcnt lgkmcnt(12)
	v_mfma_f32_32x32x16_bf16 v[34:49], v[10:13], v[94:97], v[34:49]
	v_exp_f32_e32 v142, v142
	v_exp_f32_e32 v143, v143
	v_exp_f32_e32 v144, v144
	v_exp_f32_e32 v145, v145
	ds_read_b128 v[170:173], v191 offset:4096
	ds_read_b128 v[174:177], v191 offset:4608
	s_waitcnt lgkmcnt(12)
	v_mfma_f32_32x32x16_bf16 v[18:33], v[6:9], v[118:121], v[18:33]
	v_exp_f32_e32 v66, v66
	v_exp_f32_e32 v67, v67
	v_exp_f32_e32 v68, v68
	v_exp_f32_e32 v69, v69
	ds_read_b128 v[178:181], v191 offset:6144
	ds_read_b128 v[98:101], v191 offset:6656
	s_waitcnt lgkmcnt(12)
	v_mfma_f32_32x32x16_bf16 v[34:49], v[6:9], v[122:125], v[34:49]
	v_exp_f32_e32 v70, v70
	v_exp_f32_e32 v71, v71
	v_exp_f32_e32 v72, v72
	v_exp_f32_e32 v73, v73
	s_waitcnt lgkmcnt(10)
	v_mfma_f32_32x32x16_bf16 v[18:33], v[2:5], v[102:105], v[18:33]
	v_exp_f32_e32 v74, v74
	v_exp_f32_e32 v75, v75
	v_exp_f32_e32 v76, v76
	v_exp_f32_e32 v77, v77
	s_waitcnt lgkmcnt(8)
	v_mfma_f32_32x32x16_bf16 v[34:49], v[2:5], v[90:93], v[34:49]
	v_exp_f32_e32 v78, v78
	v_exp_f32_e32 v79, v79
	v_exp_f32_e32 v80, v80
	v_exp_f32_e32 v81, v81
	s_waitcnt vmcnt(2) lgkmcnt(0)
	s_barrier
; #define WAIT_BAR(N) asm volatile("s_waitcnt vmcnt(" #N ") lgkmcnt(0)\n\ts_barrier" ::: "memory")
; #define RESC() do { if (resc) { asm volatile("s_waitcnt lgkmcnt(0)" ::: "memory"); \
;       _Pragma("unroll") for (int d_ = 0; d_ < 2; ++d_) _Pragma("unroll") for (int r = 0; r < 16; ++r) o[d_][r] *= wsf[crow(r, hi)]; } } while (0)
; #define ROT() do { sl_prev = sl_cur; sl_cur = sl_next; sl_next = (sl_next == (NSLOT - 1) * SLOTB) ? 0 : sl_next + SLOTB; } while (0)
; #define ENDW(tt) do { if ((tt) + 3 < NT) { WAIT_BAR(2); } else if ((tt) + 2 < NT) { WAIT_BAR(1); } else { WAIT_BAR(0); } } while (0)
;     ...
;     int t = 1;
;     for (; t + 5 < NT; t += 2) {
;         STEP(pB0, pB1, pA0, pA1, t, true, true, true);     WAIT_BAR(2); RESC(); ROT();
;         STEP(pA0, pA1, pB0, pB1, t + 1, true, true, true); WAIT_BAR(2); RESC(); ROT();
;     }
;     ...
;     for (; t + 1 < NT; t += 2) {
;         STEP(pB0, pB1, pA0, pA1, t, (t + 3 < NT), (t + 1 < NT), (t + 1 < NT));         ENDW(t);     RESC(); ROT();
;         STEP(pA0, pA1, pB0, pB1, t + 1, (t + 4 < NT), (t + 2 < NT), (t + 2 < NT));     ENDW(t + 1); RESC(); ROT();
	ds_read_b64_tr_b16 v[102:103], v190 offset:40960
	ds_read_b64_tr_b16 v[104:105], v190 offset:41472
	v_add_f32_e32 v2, v130, v131
	v_add_f32_e32 v2, v132, v2
	v_add_f32_e32 v2, v133, v2
	v_add_f32_e32 v2, v134, v2
	v_add_f32_e32 v2, v135, v2
	v_cvt_pk_bf16_f32 v146, v130, v131
	v_cvt_pk_bf16_f32 v147, v132, v133
	s_waitcnt lgkmcnt(9)
	v_mfma_f32_32x32x16_bf16 v[114:129], v[82:85], v[162:165], v[50:65]
	ds_read_b64_tr_b16 v[130:131], v190 offset:45056
	ds_read_b64_tr_b16 v[132:133], v190 offset:45568
	v_add_f32_e32 v2, v136, v2
	v_add_f32_e32 v2, v137, v2
	v_add_f32_e32 v2, v138, v2
	v_add_f32_e32 v2, v139, v2
	v_cvt_pk_bf16_f32 v148, v134, v135
	v_cvt_pk_bf16_f32 v149, v136, v137
	s_waitcnt lgkmcnt(10)
	v_mfma_f32_32x32x16_bf16 v[82:97], v[106:109], v[162:165], v[50:65]
	ds_read_b64_tr_b16 v[106:107], v190 offset:41984
	ds_read_b64_tr_b16 v[108:109], v190 offset:42496
	v_add_f32_e32 v2, v140, v2
	v_add_f32_e32 v2, v141, v2
	v_add_f32_e32 v2, v142, v2
	v_add_f32_e32 v2, v143, v2
	v_cvt_pk_bf16_f32 v10, v138, v139
	v_cvt_pk_bf16_f32 v11, v140, v141
	s_waitcnt lgkmcnt(11)
	v_mfma_f32_32x32x16_bf16 v[114:129], v[110:113], v[158:161], v[114:129]
	ds_read_b64_tr_b16 v[110:111], v190 offset:46080
	ds_read_b64_tr_b16 v[112:113], v190 offset:46592
	v_add_f32_e32 v2, v144, v2
	v_add_f32_e32 v2, v145, v2
	v_add_f32_e32 v2, v66, v2
	v_add_f32_e32 v2, v67, v2
	v_cvt_pk_bf16_f32 v12, v142, v143
	v_cvt_pk_bf16_f32 v13, v144, v145
	s_waitcnt lgkmcnt(12)
	v_mfma_f32_32x32x16_bf16 v[82:97], v[166:169], v[158:161], v[82:97]
	ds_read_b64_tr_b16 v[134:135], v190 offset:43008
	ds_read_b64_tr_b16 v[136:137], v190 offset:43520
	v_add_f32_e32 v2, v68, v2
	v_add_f32_e32 v2, v69, v2
	v_add_f32_e32 v2, v70, v2
	v_add_f32_e32 v2, v71, v2
	v_cvt_pk_bf16_f32 v6, v66, v67
	v_cvt_pk_bf16_f32 v7, v68, v69
	s_waitcnt lgkmcnt(13)
	v_mfma_f32_32x32x16_bf16 v[114:129], v[170:173], v[154:157], v[114:129]
	ds_read_b64_tr_b16 v[66:67], v190 offset:47104
	ds_read_b64_tr_b16 v[68:69], v190 offset:47616
	v_add_f32_e32 v2, v72, v2
	v_add_f32_e32 v2, v73, v2
	v_add_f32_e32 v2, v74, v2
	v_add_f32_e32 v2, v75, v2
	v_cvt_pk_bf16_f32 v8, v70, v71
	v_cvt_pk_bf16_f32 v9, v72, v73
	s_waitcnt lgkmcnt(14)
	v_mfma_f32_32x32x16_bf16 v[82:97], v[174:177], v[154:157], v[82:97]
	ds_read_b64_tr_b16 v[70:71], v190 offset:44032
	ds_read_b64_tr_b16 v[72:73], v190 offset:44544
	v_add_f32_e32 v2, v76, v2
	v_add_f32_e32 v2, v77, v2
	v_add_f32_e32 v2, v78, v2
	v_add_f32_e32 v138, v79, v2
	v_cvt_pk_bf16_f32 v2, v74, v75
	v_cvt_pk_bf16_f32 v3, v76, v77
	s_waitcnt lgkmcnt(14)
	v_mfma_f32_32x32x16_bf16 v[114:129], v[178:181], v[150:153], v[114:129]
	ds_read_b64_tr_b16 v[74:75], v190 offset:48128
	ds_read_b64_tr_b16 v[76:77], v190 offset:48640
	v_add_f32_e32 v4, v80, v138
	v_add_f32_e32 v4, v81, v4
	v_mfma_f32_32x32x16_bf16 v[82:97], v[98:101], v[150:153], v[82:97]
	v_add_f32_e32 v98, 0, v4
	v_cvt_pk_bf16_f32 v4, v78, v79
	v_cvt_pk_bf16_f32 v5, v80, v81
	s_add_u32 s14, s12, 0x2490000
	s_addc_u32 s15, s13, 0
	s_add_i32 s22, s22, 0x8000
	s_mov_b32 s20, m0
	s_mov_b32 m0, s22
	s_nop 0
	global_load_lds_dwordx4 v192, s[14:15]
	s_mov_b32 m0, s20
	v_add_f32_e32 v182, v194, v98
	s_waitcnt lgkmcnt(14)
	v_mfma_f32_32x32x16_bf16 v[18:33], v[146:149], v[102:105], v[18:33]
	v_exp_f32_e32 v114, v114
	v_exp_f32_e32 v115, v115
	v_exp_f32_e32 v116, v116
	v_exp_f32_e32 v117, v117
	s_waitcnt lgkmcnt(12)
	v_mfma_f32_32x32x16_bf16 v[34:49], v[146:149], v[130:133], v[34:49]
	v_exp_f32_e32 v118, v118
	v_exp_f32_e32 v119, v119
	v_exp_f32_e32 v120, v120
	v_exp_f32_e32 v121, v121
	ds_read_b128 v[78:81], v191 offset:8192
	ds_read_b128 v[138:141], v191 offset:8704
	s_waitcnt lgkmcnt(12)
	v_mfma_f32_32x32x16_bf16 v[18:33], v[10:13], v[106:109], v[18:33]
	v_exp_f32_e32 v122, v122
	v_exp_f32_e32 v123, v123
	v_exp_f32_e32 v124, v124
	v_exp_f32_e32 v125, v125
	ds_read_b128 v[142:145], v191 offset:10240
	ds_read_b128 v[166:169], v191 offset:10752
	s_waitcnt lgkmcnt(12)
	v_mfma_f32_32x32x16_bf16 v[34:49], v[10:13], v[110:113], v[34:49]
	v_exp_f32_e32 v126, v126
	v_exp_f32_e32 v127, v127
	v_exp_f32_e32 v128, v128
	v_exp_f32_e32 v129, v129
	ds_read_b128 v[170:173], v191 offset:12288
	ds_read_b128 v[174:177], v191 offset:12800
	s_waitcnt lgkmcnt(12)
	v_mfma_f32_32x32x16_bf16 v[18:33], v[6:9], v[134:137], v[18:33]
	v_exp_f32_e32 v82, v82
	v_exp_f32_e32 v83, v83
	v_exp_f32_e32 v84, v84
	v_exp_f32_e32 v85, v85
	ds_read_b128 v[134:137], v191 offset:14336
	ds_read_b128 v[130:133], v191 offset:14848
	s_waitcnt lgkmcnt(12)
	v_mfma_f32_32x32x16_bf16 v[34:49], v[6:9], v[66:69], v[34:49]
	v_exp_f32_e32 v86, v86
	v_exp_f32_e32 v87, v87
	v_exp_f32_e32 v88, v88
	v_exp_f32_e32 v89, v89
	s_waitcnt lgkmcnt(10)
	v_mfma_f32_32x32x16_bf16 v[18:33], v[2:5], v[70:73], v[18:33]
	v_exp_f32_e32 v90, v90
	v_exp_f32_e32 v91, v91
	v_exp_f32_e32 v92, v92
	v_exp_f32_e32 v93, v93
	s_waitcnt lgkmcnt(8)
	v_mfma_f32_32x32x16_bf16 v[34:49], v[2:5], v[74:77], v[34:49]
	v_exp_f32_e32 v94, v94
	v_exp_f32_e32 v95, v95
	v_exp_f32_e32 v96, v96
	v_exp_f32_e32 v97, v97
	s_waitcnt vmcnt(1) lgkmcnt(0)
	s_barrier
; #define WAIT_BAR(N) asm volatile("s_waitcnt vmcnt(" #N ") lgkmcnt(0)\n\ts_barrier" ::: "memory")
; #define RESC() do { if (resc) { asm volatile("s_waitcnt lgkmcnt(0)" ::: "memory"); \
;       _Pragma("unroll") for (int d_ = 0; d_ < 2; ++d_) _Pragma("unroll") for (int r = 0; r < 16; ++r) o[d_][r] *= wsf[crow(r, hi)]; } } while (0)
; #define ROT() do { sl_prev = sl_cur; sl_cur = sl_next; sl_next = (sl_next == (NSLOT - 1) * SLOTB) ? 0 : sl_next + SLOTB; } while (0)
; #define ENDW(tt) do { if ((tt) + 3 < NT) { WAIT_BAR(2); } else if ((tt) + 2 < NT) { WAIT_BAR(1); } else { WAIT_BAR(0); } } while (0)
;     ...
;     int t = 1;
;     for (; t + 5 < NT; t += 2) {
;         STEP(pB0, pB1, pA0, pA1, t, true, true, true);     WAIT_BAR(2); RESC(); ROT();
;         STEP(pA0, pA1, pB0, pB1, t + 1, true, true, true); WAIT_BAR(2); RESC(); ROT();
;     }
;     ...
;     for (; t + 1 < NT; t += 2) {
;         STEP(pB0, pB1, pA0, pA1, t, (t + 3 < NT), (t + 1 < NT), (t + 1 < NT));         ENDW(t);     RESC(); ROT();
;         STEP(pA0, pA1, pB0, pB1, t + 1, (t + 4 < NT), (t + 2 < NT), (t + 2 < NT));     ENDW(t + 1); RESC(); ROT();
	ds_read_b64_tr_b16 v[178:179], v190 offset:24576
	ds_read_b64_tr_b16 v[180:181], v190 offset:25088
	v_add_f32_e32 v2, v114, v115
	v_add_f32_e32 v2, v116, v2
	v_add_f32_e32 v2, v117, v2
	v_add_f32_e32 v2, v118, v2
	v_add_f32_e32 v2, v119, v2
	v_cvt_pk_bf16_f32 v146, v114, v115
	v_cvt_pk_bf16_f32 v147, v116, v117
	s_waitcnt lgkmcnt(9)
	v_mfma_f32_32x32x16_bf16 v[98:113], v[78:81], v[162:165], v[50:65]
	ds_read_b64_tr_b16 v[114:115], v190 offset:28672
	ds_read_b64_tr_b16 v[116:117], v190 offset:29184
	s_waitcnt lgkmcnt(10)
	v_mfma_f32_32x32x16_bf16 v[66:81], v[138:141], v[162:165], v[50:65]
	v_add_f32_e32 v2, v120, v2
	v_add_f32_e32 v2, v121, v2
	v_add_f32_e32 v2, v122, v2
	v_add_f32_e32 v2, v123, v2
	v_cvt_pk_bf16_f32 v148, v118, v119
	v_cvt_pk_bf16_f32 v149, v120, v121
	ds_read_b64_tr_b16 v[118:119], v190 offset:25600
	ds_read_b64_tr_b16 v[120:121], v190 offset:26112
	v_add_f32_e32 v2, v124, v2
	v_add_f32_e32 v2, v125, v2
	v_add_f32_e32 v2, v126, v2
	v_add_f32_e32 v2, v127, v2
	v_cvt_pk_bf16_f32 v10, v122, v123
	v_cvt_pk_bf16_f32 v11, v124, v125
	s_waitcnt lgkmcnt(11)
	v_mfma_f32_32x32x16_bf16 v[98:113], v[142:145], v[158:161], v[98:113]
	ds_read_b64_tr_b16 v[122:123], v190 offset:29696
	ds_read_b64_tr_b16 v[124:125], v190 offset:30208
	s_waitcnt lgkmcnt(12)
	v_mfma_f32_32x32x16_bf16 v[66:81], v[166:169], v[158:161], v[66:81]
	v_add_f32_e32 v2, v128, v2
	v_add_f32_e32 v2, v129, v2
	v_add_f32_e32 v2, v82, v2
	v_add_f32_e32 v2, v83, v2
	v_cvt_pk_bf16_f32 v12, v126, v127
	v_cvt_pk_bf16_f32 v13, v128, v129
	ds_read_b64_tr_b16 v[138:139], v190 offset:26624
	ds_read_b64_tr_b16 v[140:141], v190 offset:27136
	v_add_f32_e32 v2, v84, v2
	v_add_f32_e32 v2, v85, v2
	v_add_f32_e32 v2, v86, v2
	v_add_f32_e32 v2, v87, v2
	v_cvt_pk_bf16_f32 v6, v82, v83
	v_cvt_pk_bf16_f32 v7, v84, v85
	s_waitcnt lgkmcnt(13)
	v_mfma_f32_32x32x16_bf16 v[98:113], v[170:173], v[154:157], v[98:113]
	ds_read_b64_tr_b16 v[82:83], v190 offset:30720
	ds_read_b64_tr_b16 v[84:85], v190 offset:31232
	s_waitcnt lgkmcnt(14)
	v_mfma_f32_32x32x16_bf16 v[66:81], v[174:177], v[154:157], v[66:81]
	v_add_f32_e32 v2, v88, v2
	v_add_f32_e32 v2, v89, v2
	v_add_f32_e32 v2, v90, v2
	v_add_f32_e32 v2, v91, v2
	v_cvt_pk_bf16_f32 v8, v86, v87
	v_cvt_pk_bf16_f32 v9, v88, v89
	ds_read_b64_tr_b16 v[86:87], v190 offset:27648
	ds_read_b64_tr_b16 v[88:89], v190 offset:28160
	v_add_f32_e32 v2, v92, v2
	v_add_f32_e32 v2, v93, v2
	v_add_f32_e32 v2, v94, v2
	v_add_f32_e32 v126, v95, v2
	v_cvt_pk_bf16_f32 v2, v90, v91
	v_cvt_pk_bf16_f32 v3, v92, v93
	s_waitcnt lgkmcnt(14)
	v_mfma_f32_32x32x16_bf16 v[98:113], v[134:137], v[150:153], v[98:113]
	ds_read_b64_tr_b16 v[90:91], v190 offset:31744
	ds_read_b64_tr_b16 v[92:93], v190 offset:32256
	v_mfma_f32_32x32x16_bf16 v[66:81], v[130:133], v[150:153], v[66:81]
	v_add_f32_e32 v4, v96, v126
	v_add_f32_e32 v4, v97, v4
	v_add_f32_e32 v126, 0, v4
	v_cvt_pk_bf16_f32 v4, v94, v95
	v_cvt_pk_bf16_f32 v5, v96, v97
	s_add_u32 s12, s12, 0x24d8000
	s_addc_u32 s13, s13, 0
	s_mov_b32 s14, m0
	s_mov_b32 m0, s17
	s_nop 0
	global_load_lds_dwordx4 v192, s[12:13]
	s_mov_b32 m0, s14
	v_add_f32_e32 v126, v182, v126
	s_waitcnt lgkmcnt(14)
	v_mfma_f32_32x32x16_bf16 v[18:33], v[146:149], v[178:181], v[18:33]
	v_exp_f32_e32 v98, v98
	v_exp_f32_e32 v99, v99
	v_exp_f32_e32 v100, v100
	v_exp_f32_e32 v101, v101
	s_waitcnt lgkmcnt(12)
	v_mfma_f32_32x32x16_bf16 v[34:49], v[146:149], v[114:117], v[34:49]
	v_exp_f32_e32 v102, v102
	v_exp_f32_e32 v103, v103
	v_exp_f32_e32 v104, v104
	v_exp_f32_e32 v105, v105
	ds_read_b128 v[128:131], v191 offset:16384
	ds_read_b128 v[132:135], v191 offset:16896
	s_waitcnt lgkmcnt(12)
	v_mfma_f32_32x32x16_bf16 v[18:33], v[10:13], v[118:121], v[18:33]
	v_exp_f32_e32 v106, v106
	v_exp_f32_e32 v107, v107
	v_exp_f32_e32 v108, v108
	v_exp_f32_e32 v109, v109
	ds_read_b128 v[142:145], v191 offset:18432
	ds_read_b128 v[166:169], v191 offset:18944
	s_waitcnt lgkmcnt(12)
	v_mfma_f32_32x32x16_bf16 v[34:49], v[10:13], v[122:125], v[34:49]
	v_exp_f32_e32 v110, v110
	v_exp_f32_e32 v111, v111
	v_exp_f32_e32 v112, v112
	v_exp_f32_e32 v113, v113
	ds_read_b128 v[170:173], v191 offset:20480
	ds_read_b128 v[174:177], v191 offset:20992
	s_waitcnt lgkmcnt(12)
	v_mfma_f32_32x32x16_bf16 v[18:33], v[6:9], v[138:141], v[18:33]
	v_exp_f32_e32 v66, v66
	v_exp_f32_e32 v67, v67
	v_exp_f32_e32 v68, v68
	v_exp_f32_e32 v69, v69
	ds_read_b128 v[136:139], v191 offset:22528
	ds_read_b128 v[122:125], v191 offset:23040
	s_waitcnt lgkmcnt(12)
	v_mfma_f32_32x32x16_bf16 v[34:49], v[6:9], v[82:85], v[34:49]
	v_exp_f32_e32 v70, v70
	v_exp_f32_e32 v71, v71
	v_exp_f32_e32 v72, v72
	v_exp_f32_e32 v73, v73
	s_waitcnt lgkmcnt(10)
	v_mfma_f32_32x32x16_bf16 v[18:33], v[2:5], v[86:89], v[18:33]
	v_exp_f32_e32 v74, v74
	v_exp_f32_e32 v75, v75
	v_exp_f32_e32 v76, v76
	v_exp_f32_e32 v77, v77
	s_waitcnt lgkmcnt(8)
	v_mfma_f32_32x32x16_bf16 v[34:49], v[2:5], v[90:93], v[34:49]
	v_exp_f32_e32 v78, v78
	v_exp_f32_e32 v79, v79
	v_exp_f32_e32 v80, v80
	v_exp_f32_e32 v81, v81
	s_waitcnt vmcnt(0) lgkmcnt(0)
	s_barrier
; #define WAIT_BAR(N) asm volatile("s_waitcnt vmcnt(" #N ") lgkmcnt(0)\n\ts_barrier" ::: "memory")
; #define RESC() do { if (resc) { asm volatile("s_waitcnt lgkmcnt(0)" ::: "memory"); \
;       _Pragma("unroll") for (int d_ = 0; d_ < 2; ++d_) _Pragma("unroll") for (int r = 0; r < 16; ++r) o[d_][r] *= wsf[crow(r, hi)]; } } while (0)
; #define ROT() do { sl_prev = sl_cur; sl_cur = sl_next; sl_next = (sl_next == (NSLOT - 1) * SLOTB) ? 0 : sl_next + SLOTB; } while (0)
; #define PKW(P, B) cvtpk_s(P[B], P[B + 1])
; #define ENDW(tt) do { if ((tt) + 3 < NT) { WAIT_BAR(2); } else if ((tt) + 2 < NT) { WAIT_BAR(1); } else { WAIT_BAR(0); } } while (0)
;     ...
;     int t = 1;
;     for (; t + 5 < NT; t += 2) {
;         STEP(pB0, pB1, pA0, pA1, t, true, true, true);     WAIT_BAR(2); RESC(); ROT();
;         STEP(pA0, pA1, pB0, pB1, t + 1, true, true, true); WAIT_BAR(2); RESC(); ROT();
;     }
;     ...
;     for (; t + 1 < NT; t += 2) {
;         STEP(pB0, pB1, pA0, pA1, t, (t + 3 < NT), (t + 1 < NT), (t + 1 < NT));         ENDW(t);     RESC(); ROT();
;         STEP(pA0, pA1, pB0, pB1, t + 1, (t + 4 < NT), (t + 2 < NT), (t + 2 < NT));     ENDW(t + 1); RESC(); ROT();
;     }
;     STEP(pB0, pB1, pA0, pA1, NT - 1, false, false, false); RESC();
;     { float sacc = pB0[0] + pB0[1]; _Pragma("unroll") for (int r = 2; r < 16; ++r) sacc += pB0[r]; _Pragma("unroll") for (int r = 0; r < 16; ++r) sacc += pB1[r]; l_reg += sacc;
;       pw0 = (u32x4){PKW(pB0, 0), PKW(pB0, 2), PKW(pB0, 4), PKW(pB0, 6)}; pw1 = (u32x4){PKW(pB0, 8), PKW(pB0, 10), PKW(pB0, 12), PKW(pB0, 14)}; pw2 = (u32x4){PKW(pB1, 0), PKW(pB1, 2), PKW(pB1, 4), PKW(pB1, 6)}; pw3 = (u32x4){PKW(pB1, 8), PKW(pB1, 10), PKW(pB1, 12), PKW(pB1, 14)};
	ds_read_b64_tr_b16 v[114:115], v190 offset:32768
	ds_read_b64_tr_b16 v[116:117], v190 offset:33280
	v_add_f32_e32 v2, v98, v99
	v_add_f32_e32 v2, v100, v2
	v_add_f32_e32 v2, v101, v2
	v_add_f32_e32 v2, v102, v2
	v_add_f32_e32 v2, v103, v2
	v_cvt_pk_bf16_f32 v146, v98, v99
	v_cvt_pk_bf16_f32 v147, v100, v101
	s_waitcnt lgkmcnt(9)
	v_mfma_f32_32x32x16_bf16 v[82:97], v[128:131], v[162:165], v[50:65]
	ds_read_b64_tr_b16 v[98:99], v190 offset:36864
	ds_read_b64_tr_b16 v[100:101], v190 offset:37376
	v_add_f32_e32 v2, v104, v2
	v_add_f32_e32 v2, v105, v2
	v_add_f32_e32 v2, v106, v2
	v_add_f32_e32 v2, v107, v2
	v_cvt_pk_bf16_f32 v148, v102, v103
	v_cvt_pk_bf16_f32 v149, v104, v105
	s_waitcnt lgkmcnt(10)
	v_mfma_f32_32x32x16_bf16 v[50:65], v[132:135], v[162:165], v[50:65]
	ds_read_b64_tr_b16 v[118:119], v190 offset:33792
	ds_read_b64_tr_b16 v[120:121], v190 offset:34304
	v_add_f32_e32 v2, v108, v2
	v_add_f32_e32 v2, v109, v2
	v_add_f32_e32 v2, v110, v2
	v_add_f32_e32 v2, v111, v2
	v_cvt_pk_bf16_f32 v10, v106, v107
	v_cvt_pk_bf16_f32 v11, v108, v109
	s_waitcnt lgkmcnt(11)
	v_mfma_f32_32x32x16_bf16 v[82:97], v[142:145], v[158:161], v[82:97]
	ds_read_b64_tr_b16 v[102:103], v190 offset:37888
	ds_read_b64_tr_b16 v[104:105], v190 offset:38400
	v_add_f32_e32 v2, v112, v2
	v_add_f32_e32 v2, v113, v2
	v_add_f32_e32 v2, v66, v2
	v_add_f32_e32 v2, v67, v2
	v_cvt_pk_bf16_f32 v12, v110, v111
	v_cvt_pk_bf16_f32 v13, v112, v113
	s_waitcnt lgkmcnt(12)
	v_mfma_f32_32x32x16_bf16 v[50:65], v[166:169], v[158:161], v[50:65]
	ds_read_b64_tr_b16 v[106:107], v190 offset:34816
	ds_read_b64_tr_b16 v[108:109], v190 offset:35328
	v_add_f32_e32 v2, v68, v2
	v_add_f32_e32 v2, v69, v2
	v_add_f32_e32 v2, v70, v2
	v_add_f32_e32 v2, v71, v2
	v_cvt_pk_bf16_f32 v6, v66, v67
	v_cvt_pk_bf16_f32 v7, v68, v69
	s_waitcnt lgkmcnt(13)
	v_mfma_f32_32x32x16_bf16 v[82:97], v[170:173], v[154:157], v[82:97]
	ds_read_b64_tr_b16 v[66:67], v190 offset:38912
	ds_read_b64_tr_b16 v[68:69], v190 offset:39424
	v_add_f32_e32 v2, v72, v2
	v_add_f32_e32 v2, v73, v2
	v_add_f32_e32 v2, v74, v2
	v_add_f32_e32 v2, v75, v2
	v_cvt_pk_bf16_f32 v8, v70, v71
	v_cvt_pk_bf16_f32 v9, v72, v73
	s_waitcnt lgkmcnt(14)
	v_mfma_f32_32x32x16_bf16 v[50:65], v[174:177], v[154:157], v[50:65]
	ds_read_b64_tr_b16 v[110:111], v190 offset:35840
	ds_read_b64_tr_b16 v[112:113], v190 offset:36352
	v_add_f32_e32 v2, v76, v2
	v_add_f32_e32 v2, v77, v2
	v_add_f32_e32 v2, v78, v2
	v_add_f32_e32 v127, v79, v2
	v_cvt_pk_bf16_f32 v2, v74, v75
	v_cvt_pk_bf16_f32 v3, v76, v77
	s_waitcnt lgkmcnt(14)
	v_mfma_f32_32x32x16_bf16 v[82:97], v[136:139], v[150:153], v[82:97]
	ds_read_b64_tr_b16 v[70:71], v190 offset:39936
	ds_read_b64_tr_b16 v[72:73], v190 offset:40448
	v_add_f32_e32 v4, v80, v127
	v_add_f32_e32 v4, v81, v4
	v_add_f32_e32 v74, 0, v4
	v_cvt_pk_bf16_f32 v4, v78, v79
	v_cvt_pk_bf16_f32 v5, v80, v81
	v_mfma_f32_32x32x16_bf16 v[50:65], v[122:125], v[150:153], v[50:65]
	s_nop 3
	v_exp_f32_e32 v82, v82
	v_exp_f32_e32 v83, v83
	v_exp_f32_e32 v84, v84
	v_exp_f32_e32 v85, v85
	s_nop 0
	v_exp_f32_e32 v86, v86
	v_exp_f32_e32 v87, v87
	v_exp_f32_e32 v88, v88
	v_exp_f32_e32 v89, v89
	s_nop 0
	v_exp_f32_e32 v90, v90
	v_exp_f32_e32 v91, v91
	v_exp_f32_e32 v92, v92
	v_exp_f32_e32 v93, v93
	s_nop 0
	v_exp_f32_e32 v94, v94
	v_exp_f32_e32 v95, v95
	v_exp_f32_e32 v96, v96
	v_exp_f32_e32 v97, v97
	v_exp_f32_e32 v50, v50
	v_exp_f32_e32 v51, v51
	v_exp_f32_e32 v52, v52
	v_exp_f32_e32 v53, v53
	s_nop 0
	v_exp_f32_e32 v54, v54
	v_exp_f32_e32 v55, v55
	v_exp_f32_e32 v56, v56
	v_exp_f32_e32 v57, v57
	s_nop 0
	v_exp_f32_e32 v58, v58
	v_exp_f32_e32 v59, v59
	v_exp_f32_e32 v60, v60
	v_exp_f32_e32 v61, v61
	s_nop 0
	v_exp_f32_e32 v62, v62
	v_exp_f32_e32 v63, v63
	v_exp_f32_e32 v64, v64
	v_exp_f32_e32 v65, v65
	s_waitcnt lgkmcnt(14)
	v_mfma_f32_32x32x16_bf16 v[18:33], v[146:149], v[114:117], v[18:33]
	v_add_f32_e32 v75, v82, v83
	v_add_f32_e32 v75, v84, v75
	v_add_f32_e32 v75, v85, v75
	v_add_f32_e32 v75, v86, v75
	v_add_f32_e32 v75, v87, v75
	v_add_f32_e32 v75, v88, v75
	v_add_f32_e32 v75, v89, v75
	s_waitcnt lgkmcnt(12)
	v_mfma_f32_32x32x16_bf16 v[34:49], v[146:149], v[98:101], v[34:49]
	v_add_f32_e32 v75, v90, v75
	v_add_f32_e32 v75, v91, v75
	v_add_f32_e32 v75, v92, v75
	v_add_f32_e32 v75, v93, v75
	v_add_f32_e32 v75, v94, v75
	v_add_f32_e32 v75, v95, v75
	v_add_f32_e32 v75, v96, v75
	s_waitcnt lgkmcnt(10)
	v_mfma_f32_32x32x16_bf16 v[18:33], v[10:13], v[118:121], v[18:33]
	v_add_f32_e32 v75, v97, v75
	v_add_f32_e32 v75, v50, v75
	v_add_f32_e32 v75, v51, v75
	v_add_f32_e32 v75, v52, v75
	v_add_f32_e32 v75, v53, v75
	v_add_f32_e32 v75, v54, v75
	v_add_f32_e32 v75, v55, v75
	s_waitcnt lgkmcnt(8)
	v_mfma_f32_32x32x16_bf16 v[34:49], v[10:13], v[102:105], v[34:49]
	v_add_f32_e32 v75, v56, v75
	v_add_f32_e32 v75, v57, v75
	v_add_f32_e32 v75, v58, v75
	v_add_f32_e32 v75, v59, v75
	v_add_f32_e32 v75, v60, v75
	v_add_f32_e32 v75, v61, v75
	v_add_f32_e32 v75, v62, v75
	s_waitcnt lgkmcnt(6)
	v_mfma_f32_32x32x16_bf16 v[18:33], v[6:9], v[106:109], v[18:33]
	v_add_f32_e32 v75, v63, v75
	v_add_f32_e32 v75, v64, v75
	v_add_f32_e32 v75, v65, v75
	v_add_f32_e32 v74, v126, v74
	v_add_f32_e32 v74, v74, v75
	v_cvt_pk_bf16_f32 v76, v82, v83
	v_cvt_pk_bf16_f32 v77, v84, v85
	s_waitcnt lgkmcnt(4)
	v_mfma_f32_32x32x16_bf16 v[34:49], v[6:9], v[66:69], v[34:49]
	v_cvt_pk_bf16_f32 v78, v86, v87
	v_cvt_pk_bf16_f32 v79, v88, v89
	v_cvt_pk_bf16_f32 v10, v90, v91
	v_cvt_pk_bf16_f32 v11, v92, v93
	v_cvt_pk_bf16_f32 v12, v94, v95
	v_cvt_pk_bf16_f32 v13, v96, v97
	v_cvt_pk_bf16_f32 v6, v50, v51
	s_waitcnt lgkmcnt(2)
; __device__ __forceinline__ void pv(f32x16* o, int vb, bf16x8 pa0, bf16x8 pa1, bf16x8 pa2, bf16x8 pa3) {
; #pragma unroll
;     for (int d0 = 0; d0 < 2; ++d0) { s16x4 lo[4], hi[4];
; #pragma unroll
;         for (int ks = 0; ks < 4; ++ks) {
;             asm volatile("ds_read_b64_tr_b16 %0,%1 offset:%c2" : "=&v"(lo[ks]) : "v"(vb), "i"(d0 * 4096 + ks * 1024) : "memory");
;             asm volatile("ds_read_b64_tr_b16 %0,%1 offset:%c2" : "=&v"(hi[ks]) : "v"(vb), "i"(d0 * 4096 + ks * 1024 + 512) : "memory"); }
;         asm volatile("s_waitcnt lgkmcnt(0)" ::: "memory"); AT_SBAR();
;     ...
;         o[d0] = __builtin_amdgcn_mfma_f32_32x32x16_bf16(pa0, AT_PK(0), o[d0], 0, 0, 0);
;         o[d0] = __builtin_amdgcn_mfma_f32_32x32x16_bf16(pa1, AT_PK(1), o[d0], 0, 0, 0);
;         o[d0] = __builtin_amdgcn_mfma_f32_32x32x16_bf16(pa2, AT_PK(2), o[d0], 0, 0, 0);
;         o[d0] = __builtin_amdgcn_mfma_f32_32x32x16_bf16(pa3, AT_PK(3), o[d0], 0, 0, 0);
;     ...
;     }
; }
; __device__ __forceinline__ void store_tile(const f32x16* o, const float* rli, bf16_t* stg, bf16_t* Ow, int pitch, float* ss, int lane, int r32, int hi) {
; #pragma unroll
;     for (int r = 0; r < 16; ++r) { const int orow = crow(r, hi);
; #pragma unroll
;         for (int d0 = 0; d0 < 2; ++d0) stg[orow * 64 + d0 * 32 + r32] = (bf16_t)(cvtpk_s(o[d0][r] * rli[r], 0.f) & 0xffffu); }
;     ...
;     { float sacc = pB0[0] + pB0[1]; _Pragma("unroll") for (int r = 2; r < 16; ++r) sacc += pB0[r]; _Pragma("unroll") for (int r = 0; r < 16; ++r) sacc += pB1[r]; l_reg += sacc;
;       pw0 = (u32x4){PKW(pB0, 0), PKW(pB0, 2), PKW(pB0, 4), PKW(pB0, 6)}; pw1 = (u32x4){PKW(pB0, 8), PKW(pB0, 10), PKW(pB0, 12), PKW(pB0, 14)}; pw2 = (u32x4){PKW(pB1, 0), PKW(pB1, 2), PKW(pB1, 4), PKW(pB1, 6)}; pw3 = (u32x4){PKW(pB1, 8), PKW(pB1, 10), PKW(pB1, 12), PKW(pB1, 14)};
;       SBAR(); const int vb0 = (int)(lds0 + LDS_V) + ((lane >> 4) & 1) * 32 + (lane & 3) * 8 + (4 * hi + ((lane & 15) >> 2)) * 64;
;       at::pv(o, vb0 + sl_cur, PAF(0), PAF(1), PAF(2), PAF(3)); }
;     ...
;     { auto rr = __builtin_amdgcn_permlane32_swap(__float_as_uint(l_reg), __float_as_uint(l_reg), false, false); l_reg = __uint_as_float(rr[0]) + __uint_as_float(rr[1]); }
;     if (hi == 0) wsf[32 + r32] = l_reg; asm volatile("s_waitcnt lgkmcnt(0)" ::: "memory");
;     float rli[16];
; #pragma unroll
;     for (int r = 0; r < 16; ++r) rli[r] = __builtin_amdgcn_rcpf(wsf[32 + crow(r, hi)]);
	v_mfma_f32_32x32x16_bf16 v[18:33], v[2:5], v[110:113], v[18:33]
	v_cvt_pk_bf16_f32 v7, v52, v53
	v_cvt_pk_bf16_f32 v8, v54, v55
	v_cvt_pk_bf16_f32 v9, v56, v57
	v_cvt_pk_bf16_f32 v50, v58, v59
	v_cvt_pk_bf16_f32 v51, v60, v61
	v_cvt_pk_bf16_f32 v52, v62, v63
	v_cvt_pk_bf16_f32 v53, v64, v65
	s_waitcnt lgkmcnt(0)
	v_mfma_f32_32x32x16_bf16 v[34:49], v[2:5], v[70:73], v[34:49]
	v_add_u32_e32 v2, s16, v188
	v_add3_u32 v66, v2, v187, v189
	ds_read_b64_tr_b16 v[2:3],v66 offset:0
	ds_read_b64_tr_b16 v[4:5],v66 offset:512
	ds_read_b64_tr_b16 v[54:55],v66 offset:1024
	ds_read_b64_tr_b16 v[56:57],v66 offset:1536
	ds_read_b64_tr_b16 v[58:59],v66 offset:2048
	ds_read_b64_tr_b16 v[60:61],v66 offset:2560
	ds_read_b64_tr_b16 v[62:63],v66 offset:3072
	ds_read_b64_tr_b16 v[64:65],v66 offset:3584
	s_waitcnt lgkmcnt(0)
	s_nop 0
	v_mfma_f32_32x32x16_bf16 v[18:33], v[76:79], v[2:5], v[18:33]
	ds_read_b64_tr_b16 v[2:3],v66 offset:4096
	ds_read_b64_tr_b16 v[4:5],v66 offset:4608
	v_mfma_f32_32x32x16_bf16 v[18:33], v[10:13], v[54:57], v[18:33]
	ds_read_b64_tr_b16 v[54:55],v66 offset:5120
	ds_read_b64_tr_b16 v[56:57],v66 offset:5632
	v_mfma_f32_32x32x16_bf16 v[18:33], v[6:9], v[58:61], v[18:33]
	ds_read_b64_tr_b16 v[58:59],v66 offset:6144
	ds_read_b64_tr_b16 v[60:61],v66 offset:6656
	v_mfma_f32_32x32x16_bf16 v[18:33], v[50:53], v[62:65], v[18:33]
	ds_read_b64_tr_b16 v[62:63],v66 offset:7168
	ds_read_b64_tr_b16 v[64:65],v66 offset:7680
	s_waitcnt lgkmcnt(0)
	v_mfma_f32_32x32x16_bf16 v[34:49], v[76:79], v[2:5], v[34:49]
	v_mov_b32_e32 v2, v74
	s_nop 1
	v_permlane32_swap_b32_e32 v74, v2
	v_cmp_gt_u32_e32 vcc, 32, v15
	v_mfma_f32_32x32x16_bf16 v[34:49], v[10:13], v[54:57], v[34:49]
	v_mfma_f32_32x32x16_bf16 v[34:49], v[6:9], v[58:61], v[34:49]
	v_mfma_f32_32x32x16_bf16 v[34:49], v[50:53], v[62:65], v[34:49]
	s_and_saveexec_b64 s[12:13], vcc
	v_add_f32_e32 v2, v74, v2
	v_lshl_add_u32 v3, v17, 2, s2
	ds_write_b32 v3, v2 offset:49280
	s_or_b64 exec, exec, s[12:13]
	s_waitcnt lgkmcnt(0)
	v_lshl_add_u32 v10, v186, 4, s2
	ds_read_b128 v[2:5], v10 offset:49280
	ds_read_b128 v[6:9], v10 offset:49312
	s_lshl_b64 s[12:13], s[4:5], 11
	s_add_u32 s10, s10, s12
	s_addc_u32 s11, s11, s13
	s_lshl_b64 s[4:5], s[4:5], 4
	s_add_u32 s8, s8, s4
	s_waitcnt lgkmcnt(1)
	v_rcp_f32_e32 v11, v2
	s_addc_u32 s2, s9, s5
	s_add_u32 s6, s10, s6
	s_addc_u32 s7, s11, s7
	s_lshl_b32 s4, s19, 12
	v_rcp_f32_e32 v12, v3
	v_rcp_f32_e32 v13, v4
	v_rcp_f32_e32 v50, v5
	s_waitcnt lgkmcnt(0)
	v_rcp_f32_e32 v51, v6
	ds_read_b128 v[2:5], v10 offset:49344
	v_rcp_f32_e32 v52, v7
	v_rcp_f32_e32 v53, v8
	v_rcp_f32_e32 v54, v9
	ds_read_b128 v[6:9], v10 offset:49376
	s_add_i32 s9, s4, 0
	v_mul_f32_e32 v10, v18, v11
	v_lshlrev_b32_e32 v0, 1, v0
	v_lshlrev_b32_e32 v17, 1, v17
	v_cvt_pk_bf16_f32 v10, v10, s0
	v_add3_u32 v0, s9, v0, v17
	ds_write_b16 v0, v10 offset:51200
	v_mul_f32_e32 v10, v34, v11
	v_cvt_pk_bf16_f32 v10, v10, s0
	ds_write_b16 v0, v10 offset:51264
	v_mul_f32_e32 v10, v19, v12
	v_cvt_pk_bf16_f32 v10, v10, s0
	ds_write_b16 v0, v10 offset:51328
	v_mul_f32_e32 v10, v35, v12
	v_cvt_pk_bf16_f32 v10, v10, s0
	ds_write_b16 v0, v10 offset:51392
	v_mul_f32_e32 v10, v20, v13
	v_cvt_pk_bf16_f32 v10, v10, s0
	ds_write_b16 v0, v10 offset:51456
	v_mul_f32_e32 v10, v36, v13
	v_cvt_pk_bf16_f32 v10, v10, s0
	ds_write_b16 v0, v10 offset:51520
	v_mul_f32_e32 v10, v21, v50
	v_cvt_pk_bf16_f32 v10, v10, s0
	ds_write_b16 v0, v10 offset:51584
	v_mul_f32_e32 v10, v37, v50
	v_cvt_pk_bf16_f32 v10, v10, s0
	ds_write_b16 v0, v10 offset:51648
	v_mul_f32_e32 v10, v22, v51
	v_cvt_pk_bf16_f32 v10, v10, s0
	ds_write_b16 v0, v10 offset:52224
	v_mul_f32_e32 v10, v38, v51
	v_cvt_pk_bf16_f32 v10, v10, s0
	ds_write_b16 v0, v10 offset:52288
	v_mul_f32_e32 v10, v23, v52
	v_cvt_pk_bf16_f32 v10, v10, s0
	ds_write_b16 v0, v10 offset:52352
	v_mul_f32_e32 v10, v39, v52
	v_cvt_pk_bf16_f32 v10, v10, s0
	ds_write_b16 v0, v10 offset:52416
	v_mul_f32_e32 v10, v24, v53
	v_cvt_pk_bf16_f32 v10, v10, s0
	ds_write_b16 v0, v10 offset:52480
	v_mul_f32_e32 v10, v40, v53
	v_cvt_pk_bf16_f32 v10, v10, s0
	s_waitcnt lgkmcnt(14)
; __device__ __forceinline__ int crow(int r, int hi) { return (r & 3) + 8 * (r >> 2) + 4 * hi; }
; __device__ __forceinline__ unsigned cvtpk_s(float lo, float hi) { typedef __bf16 bf16x2_t __attribute__((ext_vector_type(2))); f32x2 v = {lo, hi}; bf16x2_t b = __builtin_convertvector(v, bf16x2_t); return __builtin_bit_cast(unsigned, b); }
; __device__ __forceinline__ void store_tile(const f32x16* o, const float* rli, bf16_t* stg, bf16_t* Ow, int pitch, float* ss, int lane, int r32, int hi) {
; #pragma unroll
;     for (int r = 0; r < 16; ++r) { const int orow = crow(r, hi);
; #pragma unroll
;         for (int d0 = 0; d0 < 2; ++d0) stg[orow * 64 + d0 * 32 + r32] = (bf16_t)(cvtpk_s(o[d0][r] * rli[r], 0.f) & 0xffffu); }
;     asm volatile("s_waitcnt lgkmcnt(0)" ::: "memory");
; #pragma unroll
;     for (int i = 0; i < 4; ++i) { const int row = i * 8 + (lane >> 3), ch = lane & 7; const u32x4 v = *(const u32x4*)(stg + row * 64 + ch * 8);
;         { const bf16_t* gp_ = Ow + (long)row * pitch + ch * 8; asm volatile("global_store_dwordx4 %0, %1, off sc0 sc1\n\ts_nop 1" :: "v"(gp_), "v"(v) : "memory"); }
;         float s = 0.f;
; #pragma unroll
;         for (int j = 0; j < 4; ++j) { const float a = __uint_as_float(v[j] << 16), b = __uint_as_float(v[j] & 0xffff0000u); s += a * a + b * b; }
;         s += __shfl_xor(s, 1); s += __shfl_xor(s, 2); s += __shfl_xor(s, 4);
;         if (ch == 0) atomicAdd(ss + (long)row * 4, s); }
;     asm volatile("s_waitcnt lgkmcnt(0)" ::: "memory");
; }
	v_rcp_f32_e32 v2, v2
	ds_write_b16 v0, v10 offset:52544
	v_mul_f32_e32 v10, v25, v54
	v_cvt_pk_bf16_f32 v10, v10, s0
	v_rcp_f32_e32 v3, v3
	ds_write_b16 v0, v10 offset:52608
	v_mul_f32_e32 v10, v41, v54
	v_cvt_pk_bf16_f32 v10, v10, s0
	ds_write_b16 v0, v10 offset:52672
	v_mul_f32_e32 v10, v26, v2
	v_mul_f32_e32 v2, v42, v2
	v_cvt_pk_bf16_f32 v2, v2, s0
	v_rcp_f32_e32 v4, v4
	ds_write_b16 v0, v2 offset:53312
	v_mul_f32_e32 v2, v27, v3
	v_cvt_pk_bf16_f32 v2, v2, s0
	ds_write_b16 v0, v2 offset:53376
	v_mul_f32_e32 v2, v43, v3
	v_cvt_pk_bf16_f32 v2, v2, s0
	v_rcp_f32_e32 v5, v5
	ds_write_b16 v0, v2 offset:53440
	v_mul_f32_e32 v2, v28, v4
	v_cvt_pk_bf16_f32 v2, v2, s0
	ds_write_b16 v0, v2 offset:53504
	v_mul_f32_e32 v2, v44, v4
	v_cvt_pk_bf16_f32 v2, v2, s0
	s_waitcnt lgkmcnt(14)
	v_rcp_f32_e32 v6, v6
	ds_write_b16 v0, v2 offset:53568
	v_mul_f32_e32 v2, v29, v5
	v_cvt_pk_bf16_f32 v2, v2, s0
	ds_write_b16 v0, v2 offset:53632
	v_mul_f32_e32 v2, v45, v5
	v_cvt_pk_bf16_f32 v2, v2, s0
	v_rcp_f32_e32 v7, v7
	ds_write_b16 v0, v2 offset:53696
	v_mul_f32_e32 v2, v30, v6
	v_cvt_pk_bf16_f32 v2, v2, s0
	ds_write_b16 v0, v2 offset:54272
	v_mul_f32_e32 v2, v46, v6
	v_cvt_pk_bf16_f32 v2, v2, s0
	v_rcp_f32_e32 v8, v8
	ds_write_b16 v0, v2 offset:54336
	v_mul_f32_e32 v2, v31, v7
	v_cvt_pk_bf16_f32 v2, v2, s0
	ds_write_b16 v0, v2 offset:54400
	v_mul_f32_e32 v2, v47, v7
	v_cvt_pk_bf16_f32 v2, v2, s0
	v_rcp_f32_e32 v9, v9
	ds_write_b16 v0, v2 offset:54464
	v_mul_f32_e32 v2, v32, v8
	v_cvt_pk_bf16_f32 v2, v2, s0
	ds_write_b16 v0, v2 offset:54528
	v_mul_f32_e32 v2, v48, v8
	v_cvt_pk_bf16_f32 v2, v2, s0
	ds_write_b16 v0, v2 offset:54592
	v_mul_f32_e32 v2, v33, v9
	v_cvt_pk_bf16_f32 v2, v2, s0
	ds_write_b16 v0, v2 offset:54656
	v_mul_f32_e32 v2, v49, v9
	v_cvt_pk_bf16_f32 v10, v10, s0
	v_cvt_pk_bf16_f32 v2, v2, s0
	v_and_b32_e32 v6, 7, v14
	ds_write_b16 v0, v10 offset:53248
	ds_write_b16 v0, v2 offset:54720
	v_lshlrev_b32_e32 v0, 4, v6
	v_lshrrev_b32_e32 v7, 3, v15
	v_add_u32_e32 v8, s9, v0
	s_waitcnt lgkmcnt(0)
	v_lshl_add_u32 v2, v7, 7, v8
	ds_read_b128 v[12:15], v2 offset:51200
	s_lshl_b64 s[4:5], s[0:1], 11
	s_add_u32 s6, s6, s4
	s_addc_u32 s7, s7, s5
	s_lshl_b64 s[0:1], s[0:1], 4
	s_waitcnt lgkmcnt(0)
	v_and_b32_e32 v3, 0xffff0000, v12
	v_lshlrev_b32_e32 v2, 16, v12
	v_mul_f32_e32 v3, v3, v3
	v_and_b32_e32 v4, 0xffff0000, v13
	v_fmac_f32_e32 v3, v2, v2
	v_lshlrev_b32_e32 v2, 16, v13
	v_mul_f32_e32 v4, v4, v4
	v_fmac_f32_e32 v4, v2, v2
	v_add_f32_e32 v2, v3, v4
	v_and_b32_e32 v4, 0xffff0000, v14
	v_lshlrev_b32_e32 v3, 16, v14
	v_mul_f32_e32 v4, v4, v4
	v_fmac_f32_e32 v4, v3, v3
	v_add_f32_e32 v2, v4, v2
	v_and_b32_e32 v4, 0xffff0000, v15
	v_lshlrev_b32_e32 v3, 16, v15
	v_mul_f32_e32 v4, v4, v4
	v_fmac_f32_e32 v4, v3, v3
	v_and_b32_e32 v3, 64, v220
	v_add_f32_e32 v5, v4, v2
	v_xor_b32_e32 v2, 1, v220
	v_add_u32_e32 v10, 64, v3
	v_cmp_lt_i32_e32 vcc, v2, v10
	s_add_u32 s0, s8, s0
	s_addc_u32 s1, s2, s1
	v_cndmask_b32_e32 v2, v220, v2, vcc
	v_lshlrev_b32_e32 v4, 2, v2
	ds_bpermute_b32 v9, v4, v5
	v_lshl_add_u64 v[2:3], s[6:7], 0, v[0:1]
	v_xor_b32_e32 v0, 2, v220
	v_cmp_lt_i32_e32 vcc, v0, v10
	s_add_u32 s4, s0, 0x200008
	s_waitcnt lgkmcnt(0)
	v_add_f32_e32 v9, v5, v9
	v_cndmask_b32_e32 v0, v220, v0, vcc
	v_lshlrev_b32_e32 v5, 2, v0
	s_addc_u32 s5, s1, 0
	ds_bpermute_b32 v11, v5, v9
	s_mov_b64 s[0:1], 0x12e40500
	v_lshl_add_u64 v[2:3], v[2:3], 0, s[0:1]
	v_lshlrev_b32_e32 v0, 11, v7
	v_lshl_add_u64 v[18:19], v[2:3], 0, v[0:1]
	v_xor_b32_e32 v0, 4, v220
	v_cmp_lt_i32_e64 s[0:1], v0, v10
	v_cmp_eq_u32_e32 vcc, 0, v6
	s_waitcnt lgkmcnt(0)
	v_add_f32_e32 v9, v9, v11
	v_cndmask_b32_e64 v0, v220, v0, s[0:1]
	v_lshlrev_b32_e32 v6, 2, v0
	ds_bpermute_b32 v10, v6, v9
	global_store_dwordx4 v[18:19], v[12:15], off sc0 sc1
	s_nop 1
	s_and_saveexec_b64 s[0:1], vcc
	v_readlane_b32 s36, v253, 25
	v_readlane_b32 s37, v253, 26
	v_readlane_b32 s38, v253, 27
	v_readlane_b32 s39, v253, 28
	v_readlane_b32 s40, v253, 29
	v_readlane_b32 s41, v253, 30
	v_readlane_b32 s42, v253, 31
	v_readlane_b32 s43, v253, 32
	v_readlane_b32 s44, v253, 33
	v_readlane_b32 s45, v253, 34
	v_readlane_b32 s46, v253, 35
	v_readlane_b32 s47, v253, 36
	v_readlane_b32 s48, v253, 37
	v_readlane_b32 s49, v253, 38
	v_readlane_b32 s50, v253, 39
	v_readlane_b32 s51, v253, 40
	s_cbranch_execz .LBB0_881
	v_lshlrev_b32_e32 v0, 4, v7
	v_lshl_add_u64 v[12:13], s[4:5], 0, v[0:1]
	s_waitcnt lgkmcnt(0)
	v_add_f32_e32 v0, v9, v10
	flat_atomic_add_f32 v[12:13], v0
